# work-queue index broadcast through ds_write/ds_read instead of flat ops (no vmcnt drain); GLA pass-3 q/k element loads flat->global with per-load counted waits instead of two mid-stream drains
# speedup vs baseline: 1.0172x; 1.0027x over previous
.LBB0_442:
	s_or_b64 exec, exec, s[8:9]
	s_waitcnt vmcnt(0)
	v_readfirstlane_b32 s8, v1
	v_mov_b32_e32 v199, v201
	s_nop 0
	v_add_u32_e32 v0, s8, v0
	ds_write_b32 v198, v0
.LBB0_443:
	s_or_b64 exec, exec, s[2:3]
	v_mov_b32_e32 v199, v201
	s_waitcnt lgkmcnt(0)
	s_barrier
	ds_read_b32 v0, v198
	s_movk_i32 s2, 0xc0
	s_waitcnt lgkmcnt(0)
	v_cmp_gt_i32_e32 vcc, s2, v0
	s_mov_b64 s[2:3], -1
	s_and_saveexec_b64 s[44:45], vcc
	s_cbranch_execz .LBB0_438
	v_ashrrev_i32_e32 v12, 6, v0
	v_and_b32_e32 v9, 31, v0
	v_lshlrev_b32_e32 v74, 1, v12
	v_mov_b32_e32 v3, v197
	v_lshrrev_b32_e32 v36, v74, v9
	v_readlane_b32 s2, v249, 40
	v_lshlrev_b32_e32 v75, 7, v36
	v_readlane_b32 s8, v249, 41
	v_ashrrev_i32_e32 v76, 1, v3
	v_and_or_b32 v15, v0, 32, s2
	v_lshlrev_b32_e64 v19, v74, -1
	v_lshl_add_u32 v0, v75, v74, s8
	v_and_b32_e32 v13, 0xffffffe0, v76
	v_bitop3_b32 v30, v0, v9, v19 bitop3:0xf4
	v_and_or_b32 v31, v3, 15, v13
	v_lshlrev_b32_e32 v0, 2, v15
	v_mov_b32_e32 v1, v2
	v_bfe_u32 v7, v3, 4, 2
	v_lshl_add_u64 v[16:17], s[4:5], 0, v[0:1]
	v_lshl_add_u32 v8, v31, v74, v30
	v_mad_i64_i32 v[4:5], s[2:3], v8, s93, v[16:17]
	v_lshlrev_b32_e32 v28, 4, v7
	v_mov_b32_e32 v29, v2
	v_lshl_add_u64 v[4:5], v[4:5], 0, v[28:29]
	global_load_dwordx4 v[20:23], v[4:5], off offset:3072
	global_load_dwordx4 v[24:27], v[4:5], off offset:3136
	v_or_b32_e32 v4, 16, v31
	v_lshl_add_u32 v4, v4, v74, v30
	v_add_u32_e32 v5, 0xffffff80, v75
	v_cmp_eq_u32_e32 vcc, 0, v36
	v_mad_i64_i32 v[16:17], s[2:3], v4, s93, v[16:17]
	s_nop 0
	v_cndmask_b32_e64 v5, v5, 0, vcc
	v_lshl_add_u64 v[16:17], v[16:17], 0, v[28:29]
	v_add_u32_e32 v5, v76, v5
	v_bitop3_b32 v77, v9, s8, v19 bitop3:0xdc
	global_load_dwordx4 v[28:31], v[16:17], off offset:3072
	global_load_dwordx4 v[32:35], v[16:17], off offset:3136
	v_lshl_add_u32 v5, v5, v74, v77
	v_mov_b64_e32 v[16:17], s[4:5]
	v_lshlrev_b32_e32 v3, 6, v3
	v_mad_i64_i32 v[16:17], s[2:3], v5, s93, v[16:17]
	v_and_b32_e32 v68, 64, v3
	v_mov_b32_e32 v69, v2
	v_lshl_add_u64 v[16:17], v[16:17], 0, v[68:69]
	v_lshl_add_u64 v[48:49], v[16:17], 0, v[0:1]
	v_or_b32_e32 v70, 0x1000, v0
	v_mov_b32_e32 v71, v2
	v_lshl_add_u64 v[16:17], v[16:17], 0, v[70:71]
	global_load_dwordx4 v[36:39], v[48:49], off offset:3632
	global_load_dwordx4 v[40:43], v[48:49], off offset:3616
	global_load_dwordx4 v[44:47], v[48:49], off offset:3600
	s_nop 0
	global_load_dwordx4 v[48:51], v[48:49], off offset:3584
	s_nop 0
	global_load_dwordx4 v[52:55], v[16:17], off offset:48
	global_load_dwordx4 v[56:59], v[16:17], off offset:32
	global_load_dwordx4 v[60:63], v[16:17], off offset:16
	global_load_dwordx4 v[64:67], v[16:17], off
	v_add_u32_e32 v3, v76, v75
	v_lshl_add_u64 v[72:73], s[4:5], 0, v[68:69]
	v_lshl_add_u32 v3, v3, v74, v77
	v_mad_i64_i32 v[72:73], s[2:3], v3, s93, v[72:73]
	v_mov_b32_e32 v3, v2
	v_or_b32_e32 v17, 31, v76
	v_lshl_add_u64 v[132:133], v[72:73], 0, v[0:1]
	v_lshl_add_u64 v[134:135], v[72:73], 0, v[70:71]
	v_mad_u64_u32 v[136:137], s[2:3], v76, s0, v[68:69]
	v_mov_b32_e32 v0, v2
	v_mov_b64_e32 v[82:83], v[2:3]
	v_mov_b64_e32 v[78:79], v[2:3]
	v_mov_b64_e32 v[74:75], v[2:3]
	v_mov_b64_e32 v[70:71], v[2:3]
	v_mov_b64_e32 v[98:99], v[2:3]
	v_mov_b64_e32 v[94:95], v[2:3]
	v_mov_b64_e32 v[90:91], v[2:3]
	v_mov_b64_e32 v[86:87], v[2:3]
	v_lshlrev_b32_e32 v16, 1, v15
	v_ashrrev_i32_e32 v9, 31, v8
	v_ashrrev_i32_e32 v5, 31, v4
	v_cndmask_b32_e64 v100, 0, 1, vcc
	v_subrev_u32_e32 v19, 63, v13
	v_add_u32_e32 v138, 0x41, v13
	v_mov_b32_e32 v137, 0
	v_mov_b32_e32 v139, 0xf149f2ca
	s_mov_b64 s[46:47], 0
	v_mov_b32_e32 v141, 0xf149f2ca
	v_mov_b32_e32 v140, 0
	v_mov_b64_e32 v[80:81], v[0:1]
	v_mov_b64_e32 v[76:77], v[0:1]
	v_mov_b64_e32 v[72:73], v[0:1]
	v_mov_b64_e32 v[68:69], v[0:1]
	v_mov_b64_e32 v[96:97], v[0:1]
	v_mov_b64_e32 v[92:93], v[0:1]
	v_mov_b64_e32 v[88:89], v[0:1]
	v_mov_b64_e32 v[84:85], v[0:1]
	s_branch .LBB0_447

.LBB0_471:
	s_or_b64 exec, exec, s[2:3]
	v_mov_b32_e32 v199, v201
	s_waitcnt lgkmcnt(0)
	s_barrier
	ds_read_b32 v8, v198
	s_movk_i32 s2, 0x200
	s_waitcnt lgkmcnt(0)
	v_cmp_gt_i32_e32 vcc, s2, v8
	s_mov_b64 s[2:3], -1
	s_and_saveexec_b64 s[40:41], vcc
	s_cbranch_execz .LBB0_466
	v_mov_b32_e32 v3, v197
	v_and_b32_e32 v7, 0x7f, v8
	v_ashrrev_i32_e32 v17, 7, v8
	v_ashrrev_i32_e32 v16, 6, v3
	v_lshlrev_b32_e32 v15, 5, v7
	v_lshl_or_b32 v9, v17, 12, v15
	v_lshlrev_b32_e32 v4, 5, v16
	v_bfe_u32 v47, v3, 5, 1
	s_movk_i32 s2, 0x1200
	v_ashrrev_i32_e32 v5, 31, v4
	v_or_b32_e32 v19, v47, v9
	v_mov_b64_e32 v[12:13], s[4:5]
	v_mul_lo_u32 v0, v16, s2
	v_and_b32_e32 v48, 31, v3
	v_mad_i64_i32 v[20:21], s[2:3], v19, s93, v[12:13]
	v_lshlrev_b64 v[52:53], 1, v[4:5]
	v_and_b32_e32 v1, 63, v3
	v_lshl_add_u64 v[20:21], v[20:21], 0, v[52:53]
	v_lshlrev_b32_e32 v54, 1, v48
	v_mov_b32_e32 v55, v2
	v_lshl_add_u64 v[20:21], v[20:21], 0, v[54:55]
	v_or_b32_e32 v58, 64, v1
	v_add_co_u32_e32 v20, vcc, s94, v20
	v_lshrrev_b32_e32 v45, 5, v58
	s_nop 0
	v_addc_co_u32_e32 v21, vcc, 0, v21, vcc
	v_or_b32_e32 v5, v45, v9
	global_load_ushort v50, v[20:21], off offset:1280
	v_mad_i64_i32 v[20:21], s[2:3], v5, s93, v[12:13]
	v_lshl_add_u64 v[20:21], v[20:21], 0, v[52:53]
	v_lshl_add_u64 v[20:21], v[20:21], 0, v[54:55]
	v_or_b32_e32 v60, 0x80, v1
	v_add_co_u32_e32 v20, vcc, s94, v20
	v_lshrrev_b32_e32 v43, 5, v60
	s_nop 0
	v_addc_co_u32_e32 v21, vcc, 0, v21, vcc
	v_or_b32_e32 v5, v43, v9
	global_load_ushort v49, v[20:21], off offset:1280
	v_mad_i64_i32 v[20:21], s[2:3], v5, s93, v[12:13]
	v_lshl_add_u64 v[20:21], v[20:21], 0, v[52:53]
	v_lshl_add_u64 v[20:21], v[20:21], 0, v[54:55]
	v_or_b32_e32 v66, 0xc0, v1
	v_add_co_u32_e32 v20, vcc, s94, v20
	v_lshrrev_b32_e32 v41, 5, v66
	s_nop 0
	v_addc_co_u32_e32 v21, vcc, 0, v21, vcc
	v_or_b32_e32 v5, v41, v9
	global_load_ushort v46, v[20:21], off offset:1280
	v_mad_i64_i32 v[20:21], s[2:3], v5, s93, v[12:13]
	v_lshl_add_u64 v[20:21], v[20:21], 0, v[52:53]
	v_lshl_add_u64 v[20:21], v[20:21], 0, v[54:55]
	v_add_co_u32_e32 v20, vcc, s94, v20
	v_or_b32_e32 v39, 8, v47
	s_nop 0
	v_addc_co_u32_e32 v21, vcc, 0, v21, vcc
	v_or_b32_e32 v5, v39, v9
	global_load_ushort v44, v[20:21], off offset:1280
	v_mad_i64_i32 v[20:21], s[2:3], v5, s93, v[12:13]
	v_lshl_add_u64 v[20:21], v[20:21], 0, v[52:53]
	v_lshl_add_u64 v[20:21], v[20:21], 0, v[54:55]
	v_add_co_u32_e32 v20, vcc, s94, v20
	v_or_b32_e32 v37, 10, v47
	s_nop 0
	v_addc_co_u32_e32 v21, vcc, 0, v21, vcc
	v_or_b32_e32 v5, v37, v9
	global_load_ushort v42, v[20:21], off offset:1280
	v_mad_i64_i32 v[20:21], s[2:3], v5, s93, v[12:13]
	v_lshl_add_u64 v[20:21], v[20:21], 0, v[52:53]
	v_lshl_add_u64 v[20:21], v[20:21], 0, v[54:55]
	v_add_co_u32_e32 v20, vcc, s94, v20
	v_or_b32_e32 v36, 12, v47
	s_nop 0
	v_addc_co_u32_e32 v21, vcc, 0, v21, vcc
	v_or_b32_e32 v5, v36, v9
	global_load_ushort v40, v[20:21], off offset:1280
	v_mad_i64_i32 v[20:21], s[2:3], v5, s93, v[12:13]
	v_lshl_add_u64 v[20:21], v[20:21], 0, v[52:53]
	v_lshl_add_u64 v[20:21], v[20:21], 0, v[54:55]
	v_add_co_u32_e32 v20, vcc, s94, v20
	v_or_b32_e32 v32, 14, v47
	s_nop 0
	v_addc_co_u32_e32 v21, vcc, 0, v21, vcc
	v_or_b32_e32 v5, v32, v9
	global_load_ushort v38, v[20:21], off offset:1280
	v_mad_i64_i32 v[20:21], s[2:3], v5, s93, v[12:13]
	v_lshl_add_u64 v[20:21], v[20:21], 0, v[52:53]
	v_lshl_add_u64 v[20:21], v[20:21], 0, v[54:55]
	v_add_co_u32_e32 v20, vcc, s94, v20
	v_or_b32_e32 v31, 16, v47
	s_nop 0
	v_addc_co_u32_e32 v21, vcc, 0, v21, vcc
	v_or_b32_e32 v5, v31, v9
	global_load_ushort v35, v[20:21], off offset:1280
	v_mad_i64_i32 v[20:21], s[2:3], v5, s93, v[12:13]
	v_lshl_add_u64 v[20:21], v[20:21], 0, v[52:53]
	v_lshl_add_u64 v[20:21], v[20:21], 0, v[54:55]
	v_add_co_u32_e32 v20, vcc, s94, v20
	v_or_b32_e32 v29, 18, v47
	s_nop 0
	v_addc_co_u32_e32 v21, vcc, 0, v21, vcc
	v_or_b32_e32 v5, v29, v9
	global_load_ushort v34, v[20:21], off offset:1280
	v_mad_i64_i32 v[20:21], s[2:3], v5, s93, v[12:13]
	v_lshl_add_u64 v[20:21], v[20:21], 0, v[52:53]
	v_lshl_add_u64 v[20:21], v[20:21], 0, v[54:55]
	v_add_co_u32_e32 v20, vcc, s94, v20
	v_or_b32_e32 v27, 20, v47
	s_nop 0
	v_addc_co_u32_e32 v21, vcc, 0, v21, vcc
	v_or_b32_e32 v5, v27, v9
	global_load_ushort v33, v[20:21], off offset:1280
	v_mad_i64_i32 v[20:21], s[2:3], v5, s93, v[12:13]
	v_lshl_add_u64 v[20:21], v[20:21], 0, v[52:53]
	v_lshl_add_u64 v[20:21], v[20:21], 0, v[54:55]
	v_add_co_u32_e32 v20, vcc, s94, v20
	v_or_b32_e32 v25, 22, v47
	s_nop 0
	v_addc_co_u32_e32 v21, vcc, 0, v21, vcc
	v_or_b32_e32 v5, v25, v9
	global_load_ushort v30, v[20:21], off offset:1280
	v_mad_i64_i32 v[20:21], s[2:3], v5, s93, v[12:13]
	v_lshl_add_u64 v[20:21], v[20:21], 0, v[52:53]
	v_lshl_add_u64 v[20:21], v[20:21], 0, v[54:55]
	v_add_co_u32_e32 v20, vcc, s94, v20
	v_or_b32_e32 v23, 24, v47
	s_nop 0
	v_addc_co_u32_e32 v21, vcc, 0, v21, vcc
	v_or_b32_e32 v5, v23, v9
	global_load_ushort v28, v[20:21], off offset:1280
	v_mad_i64_i32 v[20:21], s[2:3], v5, s93, v[12:13]
	v_lshl_add_u64 v[20:21], v[20:21], 0, v[52:53]
	v_lshl_add_u64 v[20:21], v[20:21], 0, v[54:55]
	v_add_co_u32_e32 v20, vcc, s94, v20
	v_bfe_u32 v70, v3, 3, 3
	s_nop 0
	v_addc_co_u32_e32 v21, vcc, 0, v21, vcc
	global_load_ushort v26, v[20:21], off offset:1280
	v_or_b32_e32 v21, 26, v47
	v_or_b32_e32 v5, v21, v9
	v_mad_i64_i32 v[56:57], s[2:3], v5, s93, v[12:13]
	v_lshl_add_u64 v[56:57], v[56:57], 0, v[52:53]
	v_lshl_add_u64 v[56:57], v[56:57], 0, v[54:55]
	v_add_co_u32_e32 v56, vcc, s94, v56
	v_or_b32_e32 v20, 28, v47
	s_nop 0
	v_addc_co_u32_e32 v57, vcc, 0, v57, vcc
	v_or_b32_e32 v5, v20, v9
	global_load_ushort v24, v[56:57], off offset:1280
	v_mad_i64_i32 v[56:57], s[2:3], v5, s93, v[12:13]
	v_lshl_add_u64 v[56:57], v[56:57], 0, v[52:53]
	v_lshl_add_u64 v[56:57], v[56:57], 0, v[54:55]
	v_add_co_u32_e32 v56, vcc, s94, v56
	v_or_b32_e32 v5, 30, v47
	s_nop 0
	v_addc_co_u32_e32 v57, vcc, 0, v57, vcc
	v_or_b32_e32 v19, v5, v9
	global_load_ushort v22, v[56:57], off offset:1280
	v_mad_i64_i32 v[56:57], s[2:3], v19, s93, v[12:13]
	v_lshl_add_u64 v[52:53], v[56:57], 0, v[52:53]
	v_lshl_add_u64 v[52:53], v[52:53], 0, v[54:55]
	v_add_co_u32_e32 v52, vcc, s94, v52
	v_or_b32_e32 v51, v70, v9
	s_nop 0
	v_addc_co_u32_e32 v53, vcc, 0, v53, vcc
	global_load_ushort v19, v[52:53], off offset:1280
	v_and_b32_e32 v52, 0xffffffc0, v3
	v_ashrrev_i32_e32 v53, 31, v52
	v_mad_i64_i32 v[54:55], s[2:3], v51, s93, v[12:13]
	v_lshlrev_b64 v[64:65], 1, v[52:53]
	v_lshlrev_b32_e32 v51, 4, v3
	v_lshrrev_b32_e32 v71, 3, v58
	v_lshl_add_u64 v[52:53], v[54:55], 0, v[64:65]
	v_and_b32_e32 v68, 0x70, v51
	v_mov_b32_e32 v69, v2
	v_or_b32_e32 v56, v71, v9
	v_lshl_add_u64 v[52:53], v[52:53], 0, v[68:69]
	v_mad_i64_i32 v[56:57], s[2:3], v56, s93, v[12:13]
	v_lshrrev_b32_e32 v72, 3, v60
	v_add_co_u32_e32 v52, vcc, s94, v52
	v_lshl_add_u64 v[56:57], v[56:57], 0, v[64:65]
	v_or_b32_e32 v60, v72, v9
	v_addc_co_u32_e32 v53, vcc, 0, v53, vcc
	v_lshl_add_u64 v[56:57], v[56:57], 0, v[68:69]
	v_mad_i64_i32 v[60:61], s[2:3], v60, s93, v[12:13]
	v_lshrrev_b32_e32 v73, 3, v66
	v_add_co_u32_e32 v56, vcc, s94, v56
	v_lshl_add_u64 v[60:61], v[60:61], 0, v[64:65]
	v_or_b32_e32 v66, v73, v9
	v_addc_co_u32_e32 v57, vcc, 0, v57, vcc
	v_lshl_add_u64 v[60:61], v[60:61], 0, v[68:69]
	v_mad_i64_i32 v[66:67], s[2:3], v66, s93, v[12:13]
	v_add_co_u32_e32 v60, vcc, s94, v60
	v_lshl_add_u64 v[64:65], v[66:67], 0, v[64:65]
	global_load_dwordx4 v[52:55], v[52:53], off offset:1536
	v_addc_co_u32_e32 v61, vcc, 0, v61, vcc
	v_lshl_add_u64 v[64:65], v[64:65], 0, v[68:69]
	global_load_dwordx4 v[56:59], v[56:57], off offset:1536
	v_add_co_u32_e32 v64, vcc, s94, v64
	global_load_dwordx4 v[60:63], v[60:61], off offset:1536
	s_nop 0
	v_addc_co_u32_e32 v65, vcc, 0, v65, vcc
	global_load_dwordx4 v[64:67], v[64:65], off offset:1536
	v_or_b32_e32 v68, v0, v68
	v_mad_u32_u24 v69, v70, s0, v68
	v_readlane_b32 s98, v250, 34
	v_readlane_b32 s99, v250, 35
	v_readlane_b32 s100, v250, 36
	v_readlane_b32 s101, v250, 37
	v_and_b32_e32 v236, 0x7f, v197
	v_or_b32_e32 v238, s14, v236
	v_mov_b32_e32 v239, v2
	v_lshl_add_u64 v[238:239], v[238:239], 2, s[98:99]
	v_add_co_u32_e32 v240, vcc, s94, v238
	global_load_dword v216, v[238:239], off
	global_load_dword v217, v[238:239], off offset:512
	global_load_dword v218, v[238:239], off offset:1024
	global_load_dword v219, v[238:239], off offset:1536
	global_load_dword v220, v[238:239], off offset:2048
	global_load_dword v221, v[238:239], off offset:2560
	global_load_dword v222, v[238:239], off offset:3072
	global_load_dword v223, v[238:239], off offset:3584
	v_addc_co_u32_e32 v241, vcc, 0, v239, vcc
	global_load_dword v224, v[240:241], off
	global_load_dword v225, v[240:241], off offset:512
	global_load_dword v226, v[240:241], off offset:1024
	global_load_dword v227, v[240:241], off offset:1536
	global_load_dword v228, v[240:241], off offset:2048
	global_load_dword v229, v[240:241], off offset:2560
	global_load_dword v230, v[240:241], off offset:3072
	global_load_dword v231, v[240:241], off offset:3584
	v_or_b32_e32 v238, s15, v236
	v_mov_b32_e32 v239, v2
	v_lshl_add_u64 v[238:239], v[238:239], 2, s[100:101]
	global_load_dword v232, v[238:239], off
	v_ashrrev_i32_e32 v238, 4, v197
	v_add_u32_e32 v242, 0x100, v197
	v_add_u32_e32 v238, v238, v9
	v_and_b32_e32 v240, 15, v197
	v_mad_i64_i32 v[238:239], s[2:3], v238, s93, v[12:13]
	v_lshlrev_b32_e32 v240, 1, v240
	v_mov_b32_e32 v241, v2
	v_ashrrev_i32_e32 v242, 4, v242
	v_lshl_add_u64 v[238:239], v[238:239], 0, v[240:241]
	v_add_u32_e32 v242, v242, v9
	v_mad_i64_i32 v[242:243], s[2:3], v242, s93, v[12:13]
	v_add_co_u32_e32 v238, vcc, s94, v238
	v_lshl_add_u64 v[242:243], v[242:243], 0, v[240:241]
	s_nop 0
	v_addc_co_u32_e32 v239, vcc, 0, v239, vcc
	v_add_co_u32_e32 v242, vcc, s94, v242
	global_load_ushort v233, v[238:239], off offset:2560
	s_nop 0
	v_addc_co_u32_e32 v243, vcc, 0, v243, vcc
	global_load_ushort v234, v[242:243], off offset:2560
	s_barrier
	v_readlane_b32 s44, v250, 24
	v_readlane_b32 s45, v250, 25
	v_readlane_b32 s46, v250, 26
	v_readlane_b32 s47, v250, 27
	v_readlane_b32 s48, v250, 28
	v_readlane_b32 s49, v250, 29
	v_readlane_b32 s50, v250, 30
	v_readlane_b32 s51, v250, 31
	v_readlane_b32 s52, v250, 32
	v_readlane_b32 s53, v250, 33
	v_readlane_b32 s54, v250, 34
	v_readlane_b32 s55, v250, 35
	v_readlane_b32 s56, v250, 36
	v_readlane_b32 s57, v250, 37
	v_readlane_b32 s58, v250, 38
	v_readlane_b32 s59, v250, 39
	s_mov_b64 s[44:45], s[52:53]
	s_mov_b64 s[46:47], s[54:55]
	s_mov_b64 s[48:49], s[56:57]
	s_mov_b64 s[50:51], s[58:59]
	s_waitcnt vmcnt(22)
	ds_write_b128 v69, v[52:55] offset:26624
	v_mad_u32_u24 v52, v71, s0, v68
	v_mov_b32_e32 v55, v2
	s_waitcnt vmcnt(21)
	ds_write_b128 v52, v[56:59] offset:26624
	v_mad_u32_u24 v52, v72, s0, v68
	s_waitcnt vmcnt(20)
	ds_write_b128 v52, v[60:63] offset:26624
	v_mad_u32_u24 v52, v73, s0, v68
	v_mov_b32_e32 v73, v2
	s_waitcnt vmcnt(19)
	ds_write_b128 v52, v[64:67] offset:26624
	v_mov_b32_e32 v52, v197
	s_nop 0
	v_and_b32_e32 v74, 0x7f, v52
	v_or_b32_e32 v54, s14, v74
	v_lshl_add_u64 v[54:55], v[54:55], 2, s[46:47]
	v_add_co_u32_e32 v70, vcc, s94, v54
	s_waitcnt vmcnt(0)
	v_mov_b32_e32 v66, v216
	v_mov_b32_e32 v68, v217
	v_mov_b32_e32 v64, v218
	v_mov_b32_e32 v67, v219
	v_mov_b32_e32 v60, v220
	v_mov_b32_e32 v65, v221
	v_mov_b32_e32 v59, v222
	v_mov_b32_e32 v63, v223
	v_addc_co_u32_e32 v71, vcc, 0, v55, vcc
	v_mov_b32_e32 v58, v224
	v_mov_b32_e32 v62, v225
	v_mov_b32_e32 v56, v226
	v_mov_b32_e32 v61, v227
	v_mov_b32_e32 v54, v228
	v_mov_b32_e32 v57, v229
	v_mov_b32_e32 v53, v230
	v_mov_b32_e32 v55, v231
	v_or_b32_e32 v70, s15, v74
	v_mov_b32_e32 v71, v2
	v_lshl_add_u64 v[70:71], v[70:71], 2, s[48:49]
	v_mov_b32_e32 v69, v232
	v_ashrrev_i32_e32 v70, 4, v52
	v_add_u32_e32 v75, 0x100, v52
	v_add_u32_e32 v70, v70, v9
	v_and_b32_e32 v72, 15, v52
	v_mad_i64_i32 v[70:71], s[2:3], v70, s93, v[12:13]
	v_lshlrev_b32_e32 v72, 1, v72
	v_ashrrev_i32_e32 v75, 4, v75
	v_lshl_add_u64 v[70:71], v[70:71], 0, v[72:73]
	v_add_u32_e32 v9, v75, v9
	v_mad_i64_i32 v[12:13], s[2:3], v9, s93, v[12:13]
	v_add_co_u32_e32 v70, vcc, s94, v70
	v_lshl_add_u64 v[12:13], v[12:13], 0, v[72:73]
	s_nop 0
	v_addc_co_u32_e32 v71, vcc, 0, v71, vcc
	v_add_co_u32_e32 v12, vcc, s94, v12
	v_mov_b32_e32 v9, v233
	s_nop 0
	v_addc_co_u32_e32 v13, vcc, 0, v13, vcc
	v_mov_b32_e32 v12, v234
	v_ashrrev_i32_e32 v13, 3, v52
	s_mov_b32 s2, 0xbfb8aa3b
	s_waitcnt vmcnt(1)
	v_lshlrev_b32_e32 v70, 16, v9
	v_lshlrev_b32_e32 v9, 2, v52
	s_waitcnt vmcnt(0)
	v_lshlrev_b32_e32 v12, 16, v12
	ds_write2st64_b32 v9, v70, v12 offset0:64 offset1:68
	v_and_b32_e32 v70, -16, v13
	v_lshlrev_b32_e32 v71, 6, v70
	s_waitcnt lgkmcnt(0)
	s_barrier
	v_lshlrev_b32_e32 v12, 2, v74
	ds_read_b128 v[72:75], v71 offset:16384
	ds_read_b128 v[76:79], v71 offset:16400
	ds_read_b128 v[80:83], v71 offset:16416
	ds_read_b128 v[84:87], v71 offset:16432
	v_or_b32_e32 v13, 15, v13
	s_waitcnt lgkmcnt(3)
	v_mul_f32_e32 v71, v68, v73
	v_fmac_f32_e32 v71, v66, v72
	v_mul_f32_e32 v72, v67, v75
	v_fmac_f32_e32 v72, v64, v74
	v_add_f32_e32 v71, v71, v72
	s_waitcnt lgkmcnt(2)
	v_mul_f32_e32 v72, v65, v77
	v_mul_f32_e32 v73, v63, v79
	v_fmac_f32_e32 v72, v60, v76
	v_fmac_f32_e32 v73, v59, v78
	v_add_f32_e32 v71, v69, v71
	v_add_f32_e32 v72, v72, v73
	v_add_f32_e32 v71, v71, v72
	s_waitcnt lgkmcnt(1)
	v_mul_f32_e32 v72, v62, v81
	v_mul_f32_e32 v73, v61, v83
	v_fmac_f32_e32 v72, v58, v80
	v_fmac_f32_e32 v73, v56, v82
	v_add_f32_e32 v72, v72, v73
	v_add_f32_e32 v71, v71, v72
	s_waitcnt lgkmcnt(0)
	v_mul_f32_e32 v72, v57, v85
	v_mul_f32_e32 v73, v55, v87
	v_fmac_f32_e32 v72, v54, v84
	v_fmac_f32_e32 v73, v53, v86
	v_add_f32_e32 v72, v72, v73
	v_add_f32_e32 v71, v71, v72
	v_min_f32_e32 v72, 0, v71
	v_mul_f32_e64 v71, |v71|, s2
	v_exp_f32_e32 v71, v71
	s_nop 0
	v_add_f32_e32 v71, 1.0, v71
	v_cmp_gt_f32_e32 vcc, s22, v71
	s_nop 1
	v_cndmask_b32_e64 v73, 0, 32, vcc
	v_ldexp_f32 v71, v71, v73
	v_log_f32_e32 v71, v71
	s_nop 0
	v_mul_f32_e32 v73, 0x3f317217, v71
	v_fma_f32 v73, v71, s37, -v73
	v_fmac_f32_e32 v73, 0x3377d1cf, v71
	v_fmac_f32_e32 v73, 0x3f317217, v71
	v_cmp_lt_f32_e64 s[38:39], |v71|, s1
	s_nop 1
	v_cndmask_b32_e64 v71, v71, v73, s[38:39]
	v_cndmask_b32_e32 v73, 0, v213, vcc
	v_sub_f32_e32 v71, v71, v73
	v_sub_f32_e32 v71, v72, v71
	v_mul_f32_e32 v71, 0x3d800000, v71
	v_lshl_or_b32 v72, v70, 9, v12
	ds_write_b32 v72, v71
	v_or_b32_e32 v71, 1, v70
	v_lshlrev_b32_e32 v84, 6, v71
	ds_read_b128 v[72:75], v84 offset:16384
	ds_read_b128 v[76:79], v84 offset:16400
	ds_read_b128 v[80:83], v84 offset:16416
	ds_read_b128 v[84:87], v84 offset:16432
	v_lshl_or_b32 v71, v71, 9, v12
	s_waitcnt lgkmcnt(3)
	v_mul_f32_e32 v73, v68, v73
	v_fmac_f32_e32 v73, v66, v72
	v_mul_f32_e32 v72, v67, v75
	v_fmac_f32_e32 v72, v64, v74
	v_add_f32_e32 v72, v73, v72
	s_waitcnt lgkmcnt(2)
	v_mul_f32_e32 v73, v65, v77
	v_mul_f32_e32 v74, v63, v79
	v_fmac_f32_e32 v73, v60, v76
	v_fmac_f32_e32 v74, v59, v78
	v_add_f32_e32 v72, v69, v72
	v_add_f32_e32 v73, v73, v74
	v_add_f32_e32 v72, v72, v73
	s_waitcnt lgkmcnt(1)
	v_mul_f32_e32 v73, v62, v81
	v_mul_f32_e32 v74, v61, v83
	v_fmac_f32_e32 v73, v58, v80
	v_fmac_f32_e32 v74, v56, v82
	v_add_f32_e32 v73, v73, v74
	v_add_f32_e32 v72, v72, v73
	s_waitcnt lgkmcnt(0)
	v_mul_f32_e32 v73, v57, v85
	v_mul_f32_e32 v74, v55, v87
	v_fmac_f32_e32 v73, v54, v84
	v_fmac_f32_e32 v74, v53, v86
	v_add_f32_e32 v73, v73, v74
	v_add_f32_e32 v72, v72, v73
	v_min_f32_e32 v73, 0, v72
	v_mul_f32_e64 v72, |v72|, s2
	v_exp_f32_e32 v72, v72
	s_nop 0
	v_add_f32_e32 v72, 1.0, v72
	v_cmp_gt_f32_e32 vcc, s22, v72
	s_nop 1
	v_cndmask_b32_e64 v74, 0, 32, vcc
	v_ldexp_f32 v72, v72, v74
	v_log_f32_e32 v72, v72
	s_nop 0
	v_mul_f32_e32 v74, 0x3f317217, v72
	v_fma_f32 v74, v72, s37, -v74
	v_fmac_f32_e32 v74, 0x3377d1cf, v72
	v_fmac_f32_e32 v74, 0x3f317217, v72
	v_cmp_lt_f32_e64 s[38:39], |v72|, s1
	s_nop 1
	v_cndmask_b32_e64 v72, v72, v74, s[38:39]
	v_cndmask_b32_e32 v74, 0, v213, vcc
	v_sub_f32_e32 v72, v72, v74
	v_sub_f32_e32 v72, v73, v72
	v_mul_f32_e32 v72, 0x3d800000, v72
	ds_write_b32 v71, v72
	v_or_b32_e32 v71, 2, v70
	v_lshlrev_b32_e32 v84, 6, v71
	ds_read_b128 v[72:75], v84 offset:16384
	ds_read_b128 v[76:79], v84 offset:16400
	ds_read_b128 v[80:83], v84 offset:16416
	ds_read_b128 v[84:87], v84 offset:16432
	v_lshl_or_b32 v71, v71, 9, v12
	s_waitcnt lgkmcnt(3)
	v_mul_f32_e32 v73, v68, v73
	v_fmac_f32_e32 v73, v66, v72
	v_mul_f32_e32 v72, v67, v75
	v_fmac_f32_e32 v72, v64, v74
	v_add_f32_e32 v72, v73, v72
	s_waitcnt lgkmcnt(2)
	v_mul_f32_e32 v73, v65, v77
	v_mul_f32_e32 v74, v63, v79
	v_fmac_f32_e32 v73, v60, v76
	v_fmac_f32_e32 v74, v59, v78
	v_add_f32_e32 v72, v69, v72
	v_add_f32_e32 v73, v73, v74
	v_add_f32_e32 v72, v72, v73
	s_waitcnt lgkmcnt(1)
	v_mul_f32_e32 v73, v62, v81
	v_mul_f32_e32 v74, v61, v83
	v_fmac_f32_e32 v73, v58, v80
	v_fmac_f32_e32 v74, v56, v82
	v_add_f32_e32 v73, v73, v74
	v_add_f32_e32 v72, v72, v73
	s_waitcnt lgkmcnt(0)
	v_mul_f32_e32 v73, v57, v85
	v_mul_f32_e32 v74, v55, v87
	v_fmac_f32_e32 v73, v54, v84
	v_fmac_f32_e32 v74, v53, v86
	v_add_f32_e32 v73, v73, v74
	v_add_f32_e32 v72, v72, v73
	v_min_f32_e32 v73, 0, v72
	v_mul_f32_e64 v72, |v72|, s2
	v_exp_f32_e32 v72, v72
	s_nop 0
	v_add_f32_e32 v72, 1.0, v72
	v_cmp_gt_f32_e32 vcc, s22, v72
	s_nop 1
	v_cndmask_b32_e64 v74, 0, 32, vcc
	v_ldexp_f32 v72, v72, v74
	v_log_f32_e32 v72, v72
	s_nop 0
	v_mul_f32_e32 v74, 0x3f317217, v72
	v_fma_f32 v74, v72, s37, -v74
	v_fmac_f32_e32 v74, 0x3377d1cf, v72
	v_fmac_f32_e32 v74, 0x3f317217, v72
	v_cmp_lt_f32_e64 s[38:39], |v72|, s1
	s_nop 1
	v_cndmask_b32_e64 v72, v72, v74, s[38:39]
	v_cndmask_b32_e32 v74, 0, v213, vcc
	v_sub_f32_e32 v72, v72, v74
	v_sub_f32_e32 v72, v73, v72
	v_mul_f32_e32 v72, 0x3d800000, v72
	ds_write_b32 v71, v72
	v_or_b32_e32 v71, 3, v70
	v_lshlrev_b32_e32 v84, 6, v71
	ds_read_b128 v[72:75], v84 offset:16384
	ds_read_b128 v[76:79], v84 offset:16400
	ds_read_b128 v[80:83], v84 offset:16416
	ds_read_b128 v[84:87], v84 offset:16432
	v_lshl_or_b32 v71, v71, 9, v12
	s_waitcnt lgkmcnt(3)
	v_mul_f32_e32 v73, v68, v73
	v_fmac_f32_e32 v73, v66, v72
	v_mul_f32_e32 v72, v67, v75
	v_fmac_f32_e32 v72, v64, v74
	v_add_f32_e32 v72, v73, v72
	s_waitcnt lgkmcnt(2)
	v_mul_f32_e32 v73, v65, v77
	v_mul_f32_e32 v74, v63, v79
	v_fmac_f32_e32 v73, v60, v76
	v_fmac_f32_e32 v74, v59, v78
	v_add_f32_e32 v72, v69, v72
	v_add_f32_e32 v73, v73, v74
	v_add_f32_e32 v72, v72, v73
	s_waitcnt lgkmcnt(1)
	v_mul_f32_e32 v73, v62, v81
	v_mul_f32_e32 v74, v61, v83
	v_fmac_f32_e32 v73, v58, v80
	v_fmac_f32_e32 v74, v56, v82
	v_add_f32_e32 v73, v73, v74
	v_add_f32_e32 v72, v72, v73
	s_waitcnt lgkmcnt(0)
	v_mul_f32_e32 v73, v57, v85
	v_mul_f32_e32 v74, v55, v87
	v_fmac_f32_e32 v73, v54, v84
	v_fmac_f32_e32 v74, v53, v86
	v_add_f32_e32 v73, v73, v74
	v_add_f32_e32 v72, v72, v73
	v_min_f32_e32 v73, 0, v72
	v_mul_f32_e64 v72, |v72|, s2
	v_exp_f32_e32 v72, v72
	s_nop 0
	v_add_f32_e32 v72, 1.0, v72
	v_cmp_gt_f32_e32 vcc, s22, v72
	s_nop 1
	v_cndmask_b32_e64 v74, 0, 32, vcc
	v_ldexp_f32 v72, v72, v74
	v_log_f32_e32 v72, v72
	s_nop 0
	v_mul_f32_e32 v74, 0x3f317217, v72
	v_fma_f32 v74, v72, s37, -v74
	v_fmac_f32_e32 v74, 0x3377d1cf, v72
	v_fmac_f32_e32 v74, 0x3f317217, v72
	v_cmp_lt_f32_e64 s[38:39], |v72|, s1
	s_nop 1
	v_cndmask_b32_e64 v72, v72, v74, s[38:39]
	v_cndmask_b32_e32 v74, 0, v213, vcc
	v_sub_f32_e32 v72, v72, v74
	v_sub_f32_e32 v72, v73, v72
	v_mul_f32_e32 v72, 0x3d800000, v72
	ds_write_b32 v71, v72
	v_or_b32_e32 v71, 4, v70
	v_lshlrev_b32_e32 v84, 6, v71
	ds_read_b128 v[72:75], v84 offset:16384
	ds_read_b128 v[76:79], v84 offset:16400
	ds_read_b128 v[80:83], v84 offset:16416
	ds_read_b128 v[84:87], v84 offset:16432
	v_lshl_or_b32 v71, v71, 9, v12
	s_waitcnt lgkmcnt(3)
	v_mul_f32_e32 v73, v68, v73
	v_fmac_f32_e32 v73, v66, v72
	v_mul_f32_e32 v72, v67, v75
	v_fmac_f32_e32 v72, v64, v74
	v_add_f32_e32 v72, v73, v72
	s_waitcnt lgkmcnt(2)
	v_mul_f32_e32 v73, v65, v77
	v_mul_f32_e32 v74, v63, v79
	v_fmac_f32_e32 v73, v60, v76
	v_fmac_f32_e32 v74, v59, v78
	v_add_f32_e32 v72, v69, v72
	v_add_f32_e32 v73, v73, v74
	v_add_f32_e32 v72, v72, v73
	s_waitcnt lgkmcnt(1)
	v_mul_f32_e32 v73, v62, v81
	v_mul_f32_e32 v74, v61, v83
	v_fmac_f32_e32 v73, v58, v80
	v_fmac_f32_e32 v74, v56, v82
	v_add_f32_e32 v73, v73, v74
	v_add_f32_e32 v72, v72, v73
	s_waitcnt lgkmcnt(0)
	v_mul_f32_e32 v73, v57, v85
	v_mul_f32_e32 v74, v55, v87
	v_fmac_f32_e32 v73, v54, v84
	v_fmac_f32_e32 v74, v53, v86
	v_add_f32_e32 v73, v73, v74
	v_add_f32_e32 v72, v72, v73
	v_min_f32_e32 v73, 0, v72
	v_mul_f32_e64 v72, |v72|, s2
	v_exp_f32_e32 v72, v72
	s_nop 0
	v_add_f32_e32 v72, 1.0, v72
	v_cmp_gt_f32_e32 vcc, s22, v72
	s_nop 1
	v_cndmask_b32_e64 v74, 0, 32, vcc
	v_ldexp_f32 v72, v72, v74
	v_log_f32_e32 v72, v72
	s_nop 0
	v_mul_f32_e32 v74, 0x3f317217, v72
	v_fma_f32 v74, v72, s37, -v74
	v_fmac_f32_e32 v74, 0x3377d1cf, v72
	v_fmac_f32_e32 v74, 0x3f317217, v72
	v_cmp_lt_f32_e64 s[38:39], |v72|, s1
	s_nop 1
	v_cndmask_b32_e64 v72, v72, v74, s[38:39]
	v_cndmask_b32_e32 v74, 0, v213, vcc
	v_sub_f32_e32 v72, v72, v74
	v_sub_f32_e32 v72, v73, v72
	v_mul_f32_e32 v72, 0x3d800000, v72
	ds_write_b32 v71, v72
	v_or_b32_e32 v71, 5, v70
	v_lshlrev_b32_e32 v84, 6, v71
	ds_read_b128 v[72:75], v84 offset:16384
	ds_read_b128 v[76:79], v84 offset:16400
	ds_read_b128 v[80:83], v84 offset:16416
	ds_read_b128 v[84:87], v84 offset:16432
	v_lshl_or_b32 v71, v71, 9, v12
	s_waitcnt lgkmcnt(3)
	v_mul_f32_e32 v73, v68, v73
	v_fmac_f32_e32 v73, v66, v72
	v_mul_f32_e32 v72, v67, v75
	v_fmac_f32_e32 v72, v64, v74
	v_add_f32_e32 v72, v73, v72
	s_waitcnt lgkmcnt(2)
	v_mul_f32_e32 v73, v65, v77
	v_mul_f32_e32 v74, v63, v79
	v_fmac_f32_e32 v73, v60, v76
	v_fmac_f32_e32 v74, v59, v78
	v_add_f32_e32 v72, v69, v72
	v_add_f32_e32 v73, v73, v74
	v_add_f32_e32 v72, v72, v73
	s_waitcnt lgkmcnt(1)
	v_mul_f32_e32 v73, v62, v81
	v_mul_f32_e32 v74, v61, v83
	v_fmac_f32_e32 v73, v58, v80
	v_fmac_f32_e32 v74, v56, v82
	v_add_f32_e32 v73, v73, v74
	v_add_f32_e32 v72, v72, v73
	s_waitcnt lgkmcnt(0)
	v_mul_f32_e32 v73, v57, v85
	v_mul_f32_e32 v74, v55, v87
	v_fmac_f32_e32 v73, v54, v84
	v_fmac_f32_e32 v74, v53, v86
	v_add_f32_e32 v73, v73, v74
	v_add_f32_e32 v72, v72, v73
	v_min_f32_e32 v73, 0, v72
	v_mul_f32_e64 v72, |v72|, s2
	v_exp_f32_e32 v72, v72
	s_nop 0
	v_add_f32_e32 v72, 1.0, v72
	v_cmp_gt_f32_e32 vcc, s22, v72
	s_nop 1
	v_cndmask_b32_e64 v74, 0, 32, vcc
	v_ldexp_f32 v72, v72, v74
	v_log_f32_e32 v72, v72
	s_nop 0
	v_mul_f32_e32 v74, 0x3f317217, v72
	v_fma_f32 v74, v72, s37, -v74
	v_fmac_f32_e32 v74, 0x3377d1cf, v72
	v_fmac_f32_e32 v74, 0x3f317217, v72
	v_cmp_lt_f32_e64 s[38:39], |v72|, s1
	s_nop 1
	v_cndmask_b32_e64 v72, v72, v74, s[38:39]
	v_cndmask_b32_e32 v74, 0, v213, vcc
	v_sub_f32_e32 v72, v72, v74
	v_sub_f32_e32 v72, v73, v72
	v_mul_f32_e32 v72, 0x3d800000, v72
	ds_write_b32 v71, v72
	v_or_b32_e32 v71, 6, v70
	v_lshlrev_b32_e32 v84, 6, v71
	ds_read_b128 v[72:75], v84 offset:16384
	ds_read_b128 v[76:79], v84 offset:16400
	ds_read_b128 v[80:83], v84 offset:16416
	ds_read_b128 v[84:87], v84 offset:16432
	v_lshl_or_b32 v71, v71, 9, v12
	s_waitcnt lgkmcnt(3)
	v_mul_f32_e32 v73, v68, v73
	v_fmac_f32_e32 v73, v66, v72
	v_mul_f32_e32 v72, v67, v75
	v_fmac_f32_e32 v72, v64, v74
	v_add_f32_e32 v72, v73, v72
	s_waitcnt lgkmcnt(2)
	v_mul_f32_e32 v73, v65, v77
	v_mul_f32_e32 v74, v63, v79
	v_fmac_f32_e32 v73, v60, v76
	v_fmac_f32_e32 v74, v59, v78
	v_add_f32_e32 v72, v69, v72
	v_add_f32_e32 v73, v73, v74
	v_add_f32_e32 v72, v72, v73
	s_waitcnt lgkmcnt(1)
	v_mul_f32_e32 v73, v62, v81
	v_mul_f32_e32 v74, v61, v83
	v_fmac_f32_e32 v73, v58, v80
	v_fmac_f32_e32 v74, v56, v82
	v_add_f32_e32 v73, v73, v74
	v_add_f32_e32 v72, v72, v73
	s_waitcnt lgkmcnt(0)
	v_mul_f32_e32 v73, v57, v85
	v_mul_f32_e32 v74, v55, v87
	v_fmac_f32_e32 v73, v54, v84
	v_fmac_f32_e32 v74, v53, v86
	v_add_f32_e32 v73, v73, v74
	v_add_f32_e32 v72, v72, v73
	v_min_f32_e32 v73, 0, v72
	v_mul_f32_e64 v72, |v72|, s2
	v_exp_f32_e32 v72, v72
	s_nop 0
	v_add_f32_e32 v72, 1.0, v72
	v_cmp_gt_f32_e32 vcc, s22, v72
	s_nop 1
	v_cndmask_b32_e64 v74, 0, 32, vcc
	v_ldexp_f32 v72, v72, v74
	v_log_f32_e32 v72, v72
	s_nop 0
	v_mul_f32_e32 v74, 0x3f317217, v72
	v_fma_f32 v74, v72, s37, -v74
	v_fmac_f32_e32 v74, 0x3377d1cf, v72
	v_fmac_f32_e32 v74, 0x3f317217, v72
	v_cmp_lt_f32_e64 s[38:39], |v72|, s1
	s_nop 1
	v_cndmask_b32_e64 v72, v72, v74, s[38:39]
	v_cndmask_b32_e32 v74, 0, v213, vcc
	v_sub_f32_e32 v72, v72, v74
	v_sub_f32_e32 v72, v73, v72
	v_mul_f32_e32 v72, 0x3d800000, v72
	ds_write_b32 v71, v72
	v_or_b32_e32 v71, 7, v70
	v_lshlrev_b32_e32 v84, 6, v71
	ds_read_b128 v[72:75], v84 offset:16384
	ds_read_b128 v[76:79], v84 offset:16400
	ds_read_b128 v[80:83], v84 offset:16416
	ds_read_b128 v[84:87], v84 offset:16432
	v_lshl_or_b32 v71, v71, 9, v12
	s_waitcnt lgkmcnt(3)
	v_mul_f32_e32 v73, v68, v73
	v_fmac_f32_e32 v73, v66, v72
	v_mul_f32_e32 v72, v67, v75
	v_fmac_f32_e32 v72, v64, v74
	v_add_f32_e32 v72, v73, v72
	s_waitcnt lgkmcnt(2)
	v_mul_f32_e32 v73, v65, v77
	v_mul_f32_e32 v74, v63, v79
	v_fmac_f32_e32 v73, v60, v76
	v_fmac_f32_e32 v74, v59, v78
	v_add_f32_e32 v72, v69, v72
	v_add_f32_e32 v73, v73, v74
	v_add_f32_e32 v72, v72, v73
	s_waitcnt lgkmcnt(1)
	v_mul_f32_e32 v73, v62, v81
	v_mul_f32_e32 v74, v61, v83
	v_fmac_f32_e32 v73, v58, v80
	v_fmac_f32_e32 v74, v56, v82
	v_add_f32_e32 v73, v73, v74
	v_add_f32_e32 v72, v72, v73
	s_waitcnt lgkmcnt(0)
	v_mul_f32_e32 v73, v57, v85
	v_mul_f32_e32 v74, v55, v87
	v_fmac_f32_e32 v73, v54, v84
	v_fmac_f32_e32 v74, v53, v86
	v_add_f32_e32 v73, v73, v74
	v_add_f32_e32 v72, v72, v73
	v_min_f32_e32 v73, 0, v72
	v_mul_f32_e64 v72, |v72|, s2
	v_exp_f32_e32 v72, v72
	s_nop 0
	v_add_f32_e32 v72, 1.0, v72
	v_cmp_gt_f32_e32 vcc, s22, v72
	s_nop 1
	v_cndmask_b32_e64 v74, 0, 32, vcc
	v_ldexp_f32 v72, v72, v74
	v_log_f32_e32 v72, v72
	s_nop 0
	v_mul_f32_e32 v74, 0x3f317217, v72
	v_fma_f32 v74, v72, s37, -v74
	v_fmac_f32_e32 v74, 0x3377d1cf, v72
	v_fmac_f32_e32 v74, 0x3f317217, v72
	v_cmp_lt_f32_e64 s[38:39], |v72|, s1
	s_nop 1
	v_cndmask_b32_e64 v72, v72, v74, s[38:39]
	v_cndmask_b32_e32 v74, 0, v213, vcc
	v_sub_f32_e32 v72, v72, v74
	v_sub_f32_e32 v72, v73, v72
	v_mul_f32_e32 v72, 0x3d800000, v72
	ds_write_b32 v71, v72
	v_or_b32_e32 v71, 8, v70
	v_lshlrev_b32_e32 v84, 6, v71
	ds_read_b128 v[72:75], v84 offset:16384
	ds_read_b128 v[76:79], v84 offset:16400
	ds_read_b128 v[80:83], v84 offset:16416
	ds_read_b128 v[84:87], v84 offset:16432
	v_lshl_or_b32 v71, v71, 9, v12
	s_waitcnt lgkmcnt(3)
	v_mul_f32_e32 v73, v68, v73
	v_fmac_f32_e32 v73, v66, v72
	v_mul_f32_e32 v72, v67, v75
	v_fmac_f32_e32 v72, v64, v74
	v_add_f32_e32 v72, v73, v72
	s_waitcnt lgkmcnt(2)
	v_mul_f32_e32 v73, v65, v77
	v_mul_f32_e32 v74, v63, v79
	v_fmac_f32_e32 v73, v60, v76
	v_fmac_f32_e32 v74, v59, v78
	v_add_f32_e32 v72, v69, v72
	v_add_f32_e32 v73, v73, v74
	v_add_f32_e32 v72, v72, v73
	s_waitcnt lgkmcnt(1)
	v_mul_f32_e32 v73, v62, v81
	v_mul_f32_e32 v74, v61, v83
	v_fmac_f32_e32 v73, v58, v80
	v_fmac_f32_e32 v74, v56, v82
	v_add_f32_e32 v73, v73, v74
	v_add_f32_e32 v72, v72, v73
	s_waitcnt lgkmcnt(0)
	v_mul_f32_e32 v73, v57, v85
	v_mul_f32_e32 v74, v55, v87
	v_fmac_f32_e32 v73, v54, v84
	v_fmac_f32_e32 v74, v53, v86
	v_add_f32_e32 v73, v73, v74
	v_add_f32_e32 v72, v72, v73
	v_min_f32_e32 v73, 0, v72
	v_mul_f32_e64 v72, |v72|, s2
	v_exp_f32_e32 v72, v72
	s_nop 0
	v_add_f32_e32 v72, 1.0, v72
	v_cmp_gt_f32_e32 vcc, s22, v72
	s_nop 1
	v_cndmask_b32_e64 v74, 0, 32, vcc
	v_ldexp_f32 v72, v72, v74
	v_log_f32_e32 v72, v72
	s_nop 0
	v_mul_f32_e32 v74, 0x3f317217, v72
	v_fma_f32 v74, v72, s37, -v74
	v_fmac_f32_e32 v74, 0x3377d1cf, v72
	v_fmac_f32_e32 v74, 0x3f317217, v72
	v_cmp_lt_f32_e64 s[38:39], |v72|, s1
	s_nop 1
	v_cndmask_b32_e64 v72, v72, v74, s[38:39]
	v_cndmask_b32_e32 v74, 0, v213, vcc
	v_sub_f32_e32 v72, v72, v74
	v_sub_f32_e32 v72, v73, v72
	v_mul_f32_e32 v72, 0x3d800000, v72
	ds_write_b32 v71, v72
	v_or_b32_e32 v71, 9, v70
	v_lshlrev_b32_e32 v84, 6, v71
	ds_read_b128 v[72:75], v84 offset:16384
	ds_read_b128 v[76:79], v84 offset:16400
	ds_read_b128 v[80:83], v84 offset:16416
	ds_read_b128 v[84:87], v84 offset:16432
	v_lshl_or_b32 v71, v71, 9, v12
	s_waitcnt lgkmcnt(3)
	v_mul_f32_e32 v73, v68, v73
	v_fmac_f32_e32 v73, v66, v72
	v_mul_f32_e32 v72, v67, v75
	v_fmac_f32_e32 v72, v64, v74
	v_add_f32_e32 v72, v73, v72
	s_waitcnt lgkmcnt(2)
	v_mul_f32_e32 v73, v65, v77
	v_mul_f32_e32 v74, v63, v79
	v_fmac_f32_e32 v73, v60, v76
	v_fmac_f32_e32 v74, v59, v78
	v_add_f32_e32 v72, v69, v72
	v_add_f32_e32 v73, v73, v74
	v_add_f32_e32 v72, v72, v73
	s_waitcnt lgkmcnt(1)
	v_mul_f32_e32 v73, v62, v81
	v_mul_f32_e32 v74, v61, v83
	v_fmac_f32_e32 v73, v58, v80
	v_fmac_f32_e32 v74, v56, v82
	v_add_f32_e32 v73, v73, v74
	v_add_f32_e32 v72, v72, v73
	s_waitcnt lgkmcnt(0)
	v_mul_f32_e32 v73, v57, v85
	v_mul_f32_e32 v74, v55, v87
	v_fmac_f32_e32 v73, v54, v84
	v_fmac_f32_e32 v74, v53, v86
	v_add_f32_e32 v73, v73, v74
	v_add_f32_e32 v72, v72, v73
	v_min_f32_e32 v73, 0, v72
	v_mul_f32_e64 v72, |v72|, s2
	v_exp_f32_e32 v72, v72
	s_nop 0
	v_add_f32_e32 v72, 1.0, v72
	v_cmp_gt_f32_e32 vcc, s22, v72
	s_nop 1
	v_cndmask_b32_e64 v74, 0, 32, vcc
	v_ldexp_f32 v72, v72, v74
	v_log_f32_e32 v72, v72
	s_nop 0
	v_mul_f32_e32 v74, 0x3f317217, v72
	v_fma_f32 v74, v72, s37, -v74
	v_fmac_f32_e32 v74, 0x3377d1cf, v72
	v_fmac_f32_e32 v74, 0x3f317217, v72
	v_cmp_lt_f32_e64 s[38:39], |v72|, s1
	s_nop 1
	v_cndmask_b32_e64 v72, v72, v74, s[38:39]
	v_cndmask_b32_e32 v74, 0, v213, vcc
	v_sub_f32_e32 v72, v72, v74
	v_sub_f32_e32 v72, v73, v72
	v_mul_f32_e32 v72, 0x3d800000, v72
	ds_write_b32 v71, v72
	v_or_b32_e32 v71, 10, v70
	v_lshlrev_b32_e32 v84, 6, v71
	ds_read_b128 v[72:75], v84 offset:16384
	ds_read_b128 v[76:79], v84 offset:16400
	ds_read_b128 v[80:83], v84 offset:16416
	ds_read_b128 v[84:87], v84 offset:16432
	v_lshl_or_b32 v71, v71, 9, v12
	s_waitcnt lgkmcnt(3)
	v_mul_f32_e32 v73, v68, v73
	v_fmac_f32_e32 v73, v66, v72
	v_mul_f32_e32 v72, v67, v75
	v_fmac_f32_e32 v72, v64, v74
	v_add_f32_e32 v72, v73, v72
	s_waitcnt lgkmcnt(2)
	v_mul_f32_e32 v73, v65, v77
	v_mul_f32_e32 v74, v63, v79
	v_fmac_f32_e32 v73, v60, v76
	v_fmac_f32_e32 v74, v59, v78
	v_add_f32_e32 v72, v69, v72
	v_add_f32_e32 v73, v73, v74
	v_add_f32_e32 v72, v72, v73
	s_waitcnt lgkmcnt(1)
	v_mul_f32_e32 v73, v62, v81
	v_mul_f32_e32 v74, v61, v83
	v_fmac_f32_e32 v73, v58, v80
	v_fmac_f32_e32 v74, v56, v82
	v_add_f32_e32 v73, v73, v74
	v_add_f32_e32 v72, v72, v73
	s_waitcnt lgkmcnt(0)
	v_mul_f32_e32 v73, v57, v85
	v_mul_f32_e32 v74, v55, v87
	v_fmac_f32_e32 v73, v54, v84
	v_fmac_f32_e32 v74, v53, v86
	v_add_f32_e32 v73, v73, v74
	v_add_f32_e32 v72, v72, v73
	v_min_f32_e32 v73, 0, v72
	v_mul_f32_e64 v72, |v72|, s2
	v_exp_f32_e32 v72, v72
	s_nop 0
	v_add_f32_e32 v72, 1.0, v72
	v_cmp_gt_f32_e32 vcc, s22, v72
	s_nop 1
	v_cndmask_b32_e64 v74, 0, 32, vcc
	v_ldexp_f32 v72, v72, v74
	v_log_f32_e32 v72, v72
	s_nop 0
	v_mul_f32_e32 v74, 0x3f317217, v72
	v_fma_f32 v74, v72, s37, -v74
	v_fmac_f32_e32 v74, 0x3377d1cf, v72
	v_fmac_f32_e32 v74, 0x3f317217, v72
	v_cmp_lt_f32_e64 s[38:39], |v72|, s1
	s_nop 1
	v_cndmask_b32_e64 v72, v72, v74, s[38:39]
	v_cndmask_b32_e32 v74, 0, v213, vcc
	v_sub_f32_e32 v72, v72, v74
	v_sub_f32_e32 v72, v73, v72
	v_mul_f32_e32 v72, 0x3d800000, v72
	ds_write_b32 v71, v72
	v_or_b32_e32 v71, 11, v70
	v_lshlrev_b32_e32 v84, 6, v71
	ds_read_b128 v[72:75], v84 offset:16384
	ds_read_b128 v[76:79], v84 offset:16400
	ds_read_b128 v[80:83], v84 offset:16416
	ds_read_b128 v[84:87], v84 offset:16432
	v_lshl_or_b32 v71, v71, 9, v12
	s_waitcnt lgkmcnt(3)
	v_mul_f32_e32 v73, v68, v73
	v_fmac_f32_e32 v73, v66, v72
	v_mul_f32_e32 v72, v67, v75
	v_fmac_f32_e32 v72, v64, v74
	v_add_f32_e32 v72, v73, v72
	s_waitcnt lgkmcnt(2)
	v_mul_f32_e32 v73, v65, v77
	v_mul_f32_e32 v74, v63, v79
	v_fmac_f32_e32 v73, v60, v76
	v_fmac_f32_e32 v74, v59, v78
	v_add_f32_e32 v72, v69, v72
	v_add_f32_e32 v73, v73, v74
	v_add_f32_e32 v72, v72, v73
	s_waitcnt lgkmcnt(1)
	v_mul_f32_e32 v73, v62, v81
	v_mul_f32_e32 v74, v61, v83
	v_fmac_f32_e32 v73, v58, v80
	v_fmac_f32_e32 v74, v56, v82
	v_add_f32_e32 v73, v73, v74
	v_add_f32_e32 v72, v72, v73
	s_waitcnt lgkmcnt(0)
	v_mul_f32_e32 v73, v57, v85
	v_mul_f32_e32 v74, v55, v87
	v_fmac_f32_e32 v73, v54, v84
	v_fmac_f32_e32 v74, v53, v86
	v_add_f32_e32 v73, v73, v74
	v_add_f32_e32 v72, v72, v73
	v_min_f32_e32 v73, 0, v72
	v_mul_f32_e64 v72, |v72|, s2
	v_exp_f32_e32 v72, v72
	s_nop 0
	v_add_f32_e32 v72, 1.0, v72
	v_cmp_gt_f32_e32 vcc, s22, v72
	s_nop 1
	v_cndmask_b32_e64 v74, 0, 32, vcc
	v_ldexp_f32 v72, v72, v74
	v_log_f32_e32 v72, v72
	s_nop 0
	v_mul_f32_e32 v74, 0x3f317217, v72
	v_fma_f32 v74, v72, s37, -v74
	v_fmac_f32_e32 v74, 0x3377d1cf, v72
	v_fmac_f32_e32 v74, 0x3f317217, v72
	v_cmp_lt_f32_e64 s[38:39], |v72|, s1
	s_nop 1
	v_cndmask_b32_e64 v72, v72, v74, s[38:39]
	v_cndmask_b32_e32 v74, 0, v213, vcc
	v_sub_f32_e32 v72, v72, v74
	v_sub_f32_e32 v72, v73, v72
	v_mul_f32_e32 v72, 0x3d800000, v72
	ds_write_b32 v71, v72
	v_or_b32_e32 v71, 12, v70
	v_lshlrev_b32_e32 v84, 6, v71
	ds_read_b128 v[72:75], v84 offset:16384
	ds_read_b128 v[76:79], v84 offset:16400
	ds_read_b128 v[80:83], v84 offset:16416
	ds_read_b128 v[84:87], v84 offset:16432
	v_lshl_or_b32 v71, v71, 9, v12
	s_waitcnt lgkmcnt(3)
	v_mul_f32_e32 v73, v68, v73
	v_fmac_f32_e32 v73, v66, v72
	v_mul_f32_e32 v72, v67, v75
	v_fmac_f32_e32 v72, v64, v74
	v_add_f32_e32 v72, v73, v72
	s_waitcnt lgkmcnt(2)
	v_mul_f32_e32 v73, v65, v77
	v_mul_f32_e32 v74, v63, v79
	v_fmac_f32_e32 v73, v60, v76
	v_fmac_f32_e32 v74, v59, v78
	v_add_f32_e32 v72, v69, v72
	v_add_f32_e32 v73, v73, v74
	v_add_f32_e32 v72, v72, v73
	s_waitcnt lgkmcnt(1)
	v_mul_f32_e32 v73, v62, v81
	v_mul_f32_e32 v74, v61, v83
	v_fmac_f32_e32 v73, v58, v80
	v_fmac_f32_e32 v74, v56, v82
	v_add_f32_e32 v73, v73, v74
	v_add_f32_e32 v72, v72, v73
	s_waitcnt lgkmcnt(0)
	v_mul_f32_e32 v73, v57, v85
	v_mul_f32_e32 v74, v55, v87
	v_fmac_f32_e32 v73, v54, v84
	v_fmac_f32_e32 v74, v53, v86
	v_add_f32_e32 v73, v73, v74
	v_add_f32_e32 v72, v72, v73
	v_min_f32_e32 v73, 0, v72
	v_mul_f32_e64 v72, |v72|, s2
	v_exp_f32_e32 v72, v72
	s_nop 0
	v_add_f32_e32 v72, 1.0, v72
	v_cmp_gt_f32_e32 vcc, s22, v72
	s_nop 1
	v_cndmask_b32_e64 v74, 0, 32, vcc
	v_ldexp_f32 v72, v72, v74
	v_log_f32_e32 v72, v72
	s_nop 0
	v_mul_f32_e32 v74, 0x3f317217, v72
	v_fma_f32 v74, v72, s37, -v74
	v_fmac_f32_e32 v74, 0x3377d1cf, v72
	v_fmac_f32_e32 v74, 0x3f317217, v72
	v_cmp_lt_f32_e64 s[38:39], |v72|, s1
	s_nop 1
	v_cndmask_b32_e64 v72, v72, v74, s[38:39]
	v_cndmask_b32_e32 v74, 0, v213, vcc
	v_sub_f32_e32 v72, v72, v74
	v_sub_f32_e32 v72, v73, v72
	v_mul_f32_e32 v72, 0x3d800000, v72
	ds_write_b32 v71, v72
	v_or_b32_e32 v71, 13, v70
	v_lshlrev_b32_e32 v84, 6, v71
	ds_read_b128 v[72:75], v84 offset:16384
	ds_read_b128 v[76:79], v84 offset:16400
	ds_read_b128 v[80:83], v84 offset:16416
	ds_read_b128 v[84:87], v84 offset:16432
	v_lshl_or_b32 v71, v71, 9, v12
	s_waitcnt lgkmcnt(3)
	v_mul_f32_e32 v73, v68, v73
	v_fmac_f32_e32 v73, v66, v72
	v_mul_f32_e32 v72, v67, v75
	v_fmac_f32_e32 v72, v64, v74
	v_add_f32_e32 v72, v73, v72
	s_waitcnt lgkmcnt(2)
	v_mul_f32_e32 v73, v65, v77
	v_mul_f32_e32 v74, v63, v79
	v_fmac_f32_e32 v73, v60, v76
	v_fmac_f32_e32 v74, v59, v78
	v_add_f32_e32 v72, v69, v72
	v_add_f32_e32 v73, v73, v74
	v_add_f32_e32 v72, v72, v73
	s_waitcnt lgkmcnt(1)
	v_mul_f32_e32 v73, v62, v81
	v_mul_f32_e32 v74, v61, v83
	v_fmac_f32_e32 v73, v58, v80
	v_fmac_f32_e32 v74, v56, v82
	v_add_f32_e32 v73, v73, v74
	v_add_f32_e32 v72, v72, v73
	s_waitcnt lgkmcnt(0)
	v_mul_f32_e32 v73, v57, v85
	v_mul_f32_e32 v74, v55, v87
	v_fmac_f32_e32 v73, v54, v84
	v_fmac_f32_e32 v74, v53, v86
	v_add_f32_e32 v73, v73, v74
	v_add_f32_e32 v72, v72, v73
	v_min_f32_e32 v73, 0, v72
	v_mul_f32_e64 v72, |v72|, s2
	v_exp_f32_e32 v72, v72
	v_or_b32_e32 v86, 14, v70
	v_lshlrev_b32_e32 v82, 6, v86
	v_add_f32_e32 v72, 1.0, v72
	v_cmp_gt_f32_e32 vcc, s22, v72
	s_nop 1
	v_cndmask_b32_e64 v74, 0, 32, vcc
	v_ldexp_f32 v72, v72, v74
	v_log_f32_e32 v72, v72
	s_nop 0
	v_mul_f32_e32 v74, 0x3f317217, v72
	v_fma_f32 v74, v72, s37, -v74
	v_fmac_f32_e32 v74, 0x3377d1cf, v72
	v_fmac_f32_e32 v74, 0x3f317217, v72
	v_cmp_lt_f32_e64 s[38:39], |v72|, s1
	s_nop 1
	v_cndmask_b32_e64 v72, v72, v74, s[38:39]
	v_cndmask_b32_e32 v74, 0, v213, vcc
	v_sub_f32_e32 v72, v72, v74
	v_sub_f32_e32 v72, v73, v72
	v_mul_f32_e32 v72, 0x3d800000, v72
	ds_write_b32 v71, v72
	ds_read_b128 v[70:73], v82 offset:16384
	ds_read_b128 v[74:77], v82 offset:16400
	ds_read_b128 v[78:81], v82 offset:16416
	ds_read_b128 v[82:85], v82 offset:16432
	s_waitcnt lgkmcnt(3)
	v_mul_f32_e32 v71, v68, v71
	v_fmac_f32_e32 v71, v66, v70
	v_mul_f32_e32 v70, v67, v73
	v_fmac_f32_e32 v70, v64, v72
	v_add_f32_e32 v70, v71, v70
	s_waitcnt lgkmcnt(2)
	v_mul_f32_e32 v71, v65, v75
	v_mul_f32_e32 v72, v63, v77
	v_fmac_f32_e32 v71, v60, v74
	v_fmac_f32_e32 v72, v59, v76
	v_add_f32_e32 v70, v69, v70
	v_add_f32_e32 v71, v71, v72
	v_add_f32_e32 v70, v70, v71
	s_waitcnt lgkmcnt(1)
	v_mul_f32_e32 v71, v62, v79
	v_mul_f32_e32 v72, v61, v81
	v_fmac_f32_e32 v71, v58, v78
	v_fmac_f32_e32 v72, v56, v80
	v_add_f32_e32 v71, v71, v72
	v_add_f32_e32 v70, v70, v71
	s_waitcnt lgkmcnt(0)
	v_mul_f32_e32 v71, v57, v83
	v_mul_f32_e32 v72, v55, v85
	v_fmac_f32_e32 v71, v54, v82
	v_fmac_f32_e32 v72, v53, v84
	v_add_f32_e32 v71, v71, v72
	v_add_f32_e32 v70, v70, v71
	v_min_f32_e32 v71, 0, v70
	v_mul_f32_e64 v70, |v70|, s2
	v_exp_f32_e32 v70, v70
	v_lshlrev_b32_e32 v82, 6, v13
	v_add_f32_e32 v70, 1.0, v70
	v_cmp_gt_f32_e32 vcc, s22, v70
	s_nop 1
	v_cndmask_b32_e64 v72, 0, 32, vcc
	v_ldexp_f32 v70, v70, v72
	v_log_f32_e32 v70, v70
	s_nop 0
	v_mul_f32_e32 v72, 0x3f317217, v70
	v_fma_f32 v72, v70, s37, -v72
	v_fmac_f32_e32 v72, 0x3377d1cf, v70
	v_fmac_f32_e32 v72, 0x3f317217, v70
	v_cmp_lt_f32_e64 s[38:39], |v70|, s1
	s_nop 1
	v_cndmask_b32_e64 v70, v70, v72, s[38:39]
	v_cndmask_b32_e32 v72, 0, v213, vcc
	v_sub_f32_e32 v70, v70, v72
	v_sub_f32_e32 v70, v71, v70
	v_mul_f32_e32 v70, 0x3d800000, v70
	v_lshl_or_b32 v71, v86, 9, v12
	ds_write_b32 v71, v70
	ds_read_b128 v[70:73], v82 offset:16384
	ds_read_b128 v[74:77], v82 offset:16400
	ds_read_b128 v[78:81], v82 offset:16416
	ds_read_b128 v[82:85], v82 offset:16432
	v_lshl_or_b32 v12, v13, 9, v12
	s_waitcnt lgkmcnt(3)
	v_mul_f32_e32 v68, v68, v71
	s_waitcnt lgkmcnt(2)
	v_mul_f32_e32 v65, v65, v75
	v_fmac_f32_e32 v65, v60, v74
	v_mul_f32_e32 v60, v63, v77
	v_fmac_f32_e32 v68, v66, v70
	v_mul_f32_e32 v66, v67, v73
	v_fmac_f32_e32 v60, v59, v76
	v_fmac_f32_e32 v66, v64, v72
	v_add_f32_e32 v59, v65, v60
	s_waitcnt lgkmcnt(1)
	v_mul_f32_e32 v60, v62, v79
	v_add_f32_e32 v64, v68, v66
	v_fmac_f32_e32 v60, v58, v78
	v_mul_f32_e32 v58, v61, v81
	s_waitcnt lgkmcnt(0)
	v_mul_f32_e32 v57, v57, v83
	v_add_f32_e32 v64, v69, v64
	v_fmac_f32_e32 v58, v56, v80
	v_fmac_f32_e32 v57, v54, v82
	v_mul_f32_e32 v54, v55, v85
	v_add_f32_e32 v59, v64, v59
	v_add_f32_e32 v56, v60, v58
	v_fmac_f32_e32 v54, v53, v84
	v_add_f32_e32 v56, v59, v56
	v_add_f32_e32 v53, v57, v54
	v_add_f32_e32 v53, v56, v53
	v_min_f32_e32 v54, 0, v53
	v_mul_f32_e64 v53, |v53|, s2
	v_exp_f32_e32 v53, v53
	s_movk_i32 s2, 0x80
	v_add_f32_e32 v53, 1.0, v53
	v_cmp_gt_f32_e32 vcc, s22, v53
	s_nop 1
	v_cndmask_b32_e64 v55, 0, 32, vcc
	v_ldexp_f32 v53, v53, v55
	v_log_f32_e32 v53, v53
	s_nop 0
	v_mul_f32_e32 v55, 0x3f317217, v53
	v_fma_f32 v55, v53, s37, -v55
	v_fmac_f32_e32 v55, 0x3377d1cf, v53
	v_fmac_f32_e32 v55, 0x3f317217, v53
	v_cmp_lt_f32_e64 s[38:39], |v53|, s1
	s_nop 1
	v_cndmask_b32_e64 v53, v53, v55, s[38:39]
	v_cndmask_b32_e32 v55, 0, v213, vcc
	v_sub_f32_e32 v53, v53, v55
	v_sub_f32_e32 v53, v54, v53
	v_mul_f32_e32 v53, 0x3d800000, v53
	v_cmp_gt_i32_e32 vcc, s2, v52
	ds_write_b32 v12, v53
	s_waitcnt lgkmcnt(0)
	s_barrier
	s_and_saveexec_b64 s[2:3], vcc
	s_cbranch_execz .LBB0_474
	ds_read2st64_b32 v[12:13], v9 offset1:2
	s_waitcnt lgkmcnt(0)
	v_add_f32_e32 v12, 0, v12
	v_add_f32_e32 v52, v12, v13
	ds_write2st64_b32 v9, v12, v52 offset1:2
	ds_read2st64_b32 v[12:13], v9 offset0:4 offset1:6
	s_waitcnt lgkmcnt(0)
	v_add_f32_e32 v12, v52, v12
	v_add_f32_e32 v52, v12, v13
	ds_write2st64_b32 v9, v12, v52 offset0:4 offset1:6
	ds_read2st64_b32 v[12:13], v9 offset0:8 offset1:10
	s_waitcnt lgkmcnt(0)
	v_add_f32_e32 v12, v52, v12
	v_add_f32_e32 v52, v12, v13
	ds_write2st64_b32 v9, v12, v52 offset0:8 offset1:10
	ds_read2st64_b32 v[12:13], v9 offset0:12 offset1:14
	s_waitcnt lgkmcnt(0)
	v_add_f32_e32 v12, v52, v12
	v_add_f32_e32 v52, v12, v13
	ds_write2st64_b32 v9, v12, v52 offset0:12 offset1:14
	ds_read2st64_b32 v[12:13], v9 offset0:16 offset1:18
	s_waitcnt lgkmcnt(0)
	v_add_f32_e32 v12, v52, v12
	v_add_f32_e32 v52, v12, v13
	ds_write2st64_b32 v9, v12, v52 offset0:16 offset1:18
	ds_read2st64_b32 v[12:13], v9 offset0:20 offset1:22
	s_waitcnt lgkmcnt(0)
	v_add_f32_e32 v12, v52, v12
	v_add_f32_e32 v52, v12, v13
	ds_write2st64_b32 v9, v12, v52 offset0:20 offset1:22
	ds_read2st64_b32 v[12:13], v9 offset0:24 offset1:26
	s_waitcnt lgkmcnt(0)
	v_add_f32_e32 v12, v52, v12
	v_add_f32_e32 v52, v12, v13
	ds_write2st64_b32 v9, v12, v52 offset0:24 offset1:26
	ds_read2st64_b32 v[12:13], v9 offset0:28 offset1:30
	s_waitcnt lgkmcnt(0)
	v_add_f32_e32 v12, v52, v12
	v_add_f32_e32 v52, v12, v13
	ds_write2st64_b32 v9, v12, v52 offset0:28 offset1:30
	ds_read2st64_b32 v[12:13], v9 offset0:32 offset1:34
	s_waitcnt lgkmcnt(0)
	v_add_f32_e32 v12, v52, v12
	v_add_f32_e32 v52, v12, v13
	ds_write2st64_b32 v9, v12, v52 offset0:32 offset1:34
	ds_read2st64_b32 v[12:13], v9 offset0:36 offset1:38
	s_waitcnt lgkmcnt(0)
	v_add_f32_e32 v12, v52, v12
	v_add_f32_e32 v52, v12, v13
	ds_write2st64_b32 v9, v12, v52 offset0:36 offset1:38
	ds_read2st64_b32 v[12:13], v9 offset0:40 offset1:42
	s_waitcnt lgkmcnt(0)
	v_add_f32_e32 v12, v52, v12
	v_add_f32_e32 v52, v12, v13
	ds_write2st64_b32 v9, v12, v52 offset0:40 offset1:42
	ds_read2st64_b32 v[12:13], v9 offset0:44 offset1:46
	s_waitcnt lgkmcnt(0)
	v_add_f32_e32 v12, v52, v12
	v_add_f32_e32 v52, v12, v13
	ds_write2st64_b32 v9, v12, v52 offset0:44 offset1:46
	ds_read2st64_b32 v[12:13], v9 offset0:48 offset1:50
	s_waitcnt lgkmcnt(0)
	v_add_f32_e32 v12, v52, v12
	v_add_f32_e32 v52, v12, v13
	ds_write2st64_b32 v9, v12, v52 offset0:48 offset1:50
	ds_read2st64_b32 v[12:13], v9 offset0:52 offset1:54
	s_waitcnt lgkmcnt(0)
	v_add_f32_e32 v12, v52, v12
	v_add_f32_e32 v52, v12, v13
	ds_write2st64_b32 v9, v12, v52 offset0:52 offset1:54
	ds_read2st64_b32 v[12:13], v9 offset0:56 offset1:58
	s_waitcnt lgkmcnt(0)
	v_add_f32_e32 v12, v52, v12
	v_add_f32_e32 v52, v12, v13
	ds_write2st64_b32 v9, v12, v52 offset0:56 offset1:58
	ds_read2st64_b32 v[12:13], v9 offset0:60 offset1:62
	s_waitcnt lgkmcnt(0)
	v_add_f32_e32 v12, v52, v12
	v_add_f32_e32 v13, v12, v13
	ds_write2st64_b32 v9, v12, v13 offset0:60 offset1:62

.LBB0_585:
	s_ashr_i32 s3, s44, 7
	s_and_b32 s8, s44, 0x7f
	v_mov_b32_e32 v15, v197
	s_lshl_b32 s2, s3, 12
	s_lshl_b32 s9, s8, 5
	s_or_b32 s2, s2, s9
	v_and_b32_e32 v130, 15, v197
	v_or_b32_e32 v130, s2, v130
	v_mov_b64_e32 v[132:133], s[4:5]
	v_mad_i64_i32 v[132:133], s[100:101], v130, s93, v[132:133]
	v_lshrrev_b32_e32 v131, 6, v197
	v_lshlrev_b32_e32 v131, 7, v131
	v_bfe_u32 v134, v197, 4, 2
	v_lshl_add_u32 v131, v134, 3, v131
	v_add_u32_e32 v134, 0x1800, v131
	v_mov_b32_e32 v135, 0
	v_lshl_add_u64 v[132:133], v[132:133], 0, v[134:135]
	global_load_dwordx2 v[136:137], v[132:133], off
	global_load_dwordx2 v[138:139], v[132:133], off offset:32
	global_load_dwordx2 v[140:141], v[132:133], off offset:64
	global_load_dwordx2 v[142:143], v[132:133], off offset:96
	s_mov_b64 s[100:101], 0x1a800
	v_lshl_add_u64 v[132:133], v[132:133], 0, s[100:101]
	v_and_b32_e32 v152, 48, v197
	global_load_dwordx4 v[156:159], v152, s[42:43]
	global_load_dwordx4 v[160:163], v152, s[42:43] offset:64
	global_load_dwordx4 v[164:167], v152, s[42:43] offset:128
	global_load_dwordx4 v[168:171], v152, s[42:43] offset:192
	global_load_dwordx2 v[144:145], v[132:133], off
	global_load_dwordx2 v[146:147], v[132:133], off offset:32
	global_load_dwordx2 v[148:149], v[132:133], off offset:64
	global_load_dwordx2 v[150:151], v[132:133], off offset:96
	v_ashrrev_i32_e32 v1, 6, v15
	v_bfe_u32 v4, v15, 5, 1
	v_or_b32_e32 v8, s2, v4
	v_mov_b64_e32 v[4:5], s[4:5]
	v_lshlrev_b32_e32 v16, 5, v1
	v_lshlrev_b32_e32 v0, 11, v1
	s_movk_i32 s9, 0xa00
	v_mad_i64_i32 v[8:9], s[10:11], v8, s93, v[4:5]
	v_ashrrev_i32_e32 v17, 31, v16
	v_and_b32_e32 v19, 31, v15
	v_mad_u64_u32 v[12:13], s[10:11], v1, s9, v[0:1]
	v_lshl_add_u64 v[8:9], v[16:17], 1, v[8:9]
	v_lshlrev_b32_e32 v16, 1, v19
	v_mov_b32_e32 v17, v2
	v_lshl_add_u64 v[8:9], v[8:9], 0, v[16:17]
	s_mov_b64 s[10:11], 0x3500
	v_lshl_add_u64 v[16:17], v[8:9], 0, s[10:11]
	v_add_co_u32_e32 v8, vcc, s94, v8
	v_bfe_u32 v89, v15, 3, 3
	s_nop 0
	v_addc_co_u32_e32 v9, vcc, 0, v9, vcc
	global_load_ushort v87, v[8:9], off offset:1024
	global_load_ushort v86, v[8:9], off offset:1280
	v_lshlrev_b32_e32 v88, 4, v15
	v_lshl_add_u64 v[8:9], v[16:17], 0, s[10:11]
	v_add_co_u32_e32 v16, vcc, s94, v16
	v_and_b32_e32 v3, 63, v15
	s_nop 0
	v_addc_co_u32_e32 v17, vcc, 0, v17, vcc
	global_load_ushort v85, v[16:17], off offset:1024
	global_load_ushort v84, v[16:17], off offset:1280
	v_or_b32_e32 v74, 64, v3
	v_lshl_add_u64 v[16:17], v[8:9], 0, s[10:11]
	v_add_co_u32_e32 v8, vcc, s94, v8
	v_lshrrev_b32_e32 v122, 3, v74
	s_nop 0
	v_addc_co_u32_e32 v9, vcc, 0, v9, vcc
	global_load_ushort v83, v[8:9], off offset:1024
	global_load_ushort v82, v[8:9], off offset:1280
	v_or_b32_e32 v75, 0x80, v3
	v_lshl_add_u64 v[8:9], v[16:17], 0, s[10:11]
	v_add_co_u32_e32 v16, vcc, s94, v16
	v_lshrrev_b32_e32 v123, 3, v75
	s_nop 0
	v_addc_co_u32_e32 v17, vcc, 0, v17, vcc
	global_load_ushort v81, v[16:17], off offset:1024
	global_load_ushort v80, v[16:17], off offset:1280
	v_or_b32_e32 v76, 0xc0, v3
	v_lshl_add_u64 v[16:17], v[8:9], 0, s[10:11]
	v_add_co_u32_e32 v8, vcc, s94, v8
	v_lshrrev_b32_e32 v124, 3, v76
	s_nop 0
	v_addc_co_u32_e32 v9, vcc, 0, v9, vcc
	global_load_ushort v79, v[8:9], off offset:1024
	global_load_ushort v78, v[8:9], off offset:1280
	s_ashr_i32 s45, s44, 31
	v_lshl_add_u64 v[8:9], v[16:17], 0, s[10:11]
	v_add_co_u32_e32 v16, vcc, s94, v16
	v_lshlrev_b32_e32 v22, 4, v3
	s_nop 0
	v_addc_co_u32_e32 v17, vcc, 0, v17, vcc
	global_load_ushort v77, v[16:17], off offset:1024
	global_load_ushort v73, v[16:17], off offset:1280
	v_mov_b32_e32 v23, v2
	v_lshl_add_u64 v[16:17], v[8:9], 0, s[10:11]
	v_add_co_u32_e32 v8, vcc, s94, v8
	v_lshlrev_b32_e32 v118, 2, v15
	s_nop 0
	v_addc_co_u32_e32 v9, vcc, 0, v9, vcc
	global_load_ushort v72, v[8:9], off offset:1024
	global_load_ushort v71, v[8:9], off offset:1280
	v_ashrrev_i32_e32 v119, 31, v118
	v_lshl_add_u64 v[8:9], v[16:17], 0, s[10:11]
	v_add_co_u32_e32 v16, vcc, s94, v16
	v_add_u32_e32 v110, 0x400, v118
	s_nop 0
	v_addc_co_u32_e32 v17, vcc, 0, v17, vcc
	global_load_ushort v70, v[16:17], off offset:1024
	global_load_ushort v69, v[16:17], off offset:1280
	v_ashrrev_i32_e32 v111, 31, v110
	v_lshl_add_u64 v[16:17], v[8:9], 0, s[10:11]
	v_add_co_u32_e32 v8, vcc, s94, v8
	v_add_u32_e32 v114, 0x800, v118
	s_nop 0
	v_addc_co_u32_e32 v9, vcc, 0, v9, vcc
	global_load_ushort v68, v[8:9], off offset:1024
	global_load_ushort v67, v[8:9], off offset:1280
	v_ashrrev_i32_e32 v115, 31, v114
	v_lshl_add_u64 v[8:9], v[16:17], 0, s[10:11]
	v_add_co_u32_e32 v16, vcc, s94, v16
	v_lshlrev_b32_e32 v13, 3, v15
	s_nop 0
	v_addc_co_u32_e32 v17, vcc, 0, v17, vcc
	global_load_ushort v66, v[16:17], off offset:1024
	global_load_ushort v65, v[16:17], off offset:1280
	s_waitcnt vmcnt(18)
	v_lshlrev_b32_e32 v86, 16, v86
	v_lshl_add_u64 v[16:17], v[8:9], 0, s[10:11]
	v_add_co_u32_e32 v8, vcc, s94, v8
	s_waitcnt vmcnt(19)
	v_lshlrev_b32_e32 v87, 16, v87
	s_nop 0
	v_addc_co_u32_e32 v9, vcc, 0, v9, vcc
	global_load_ushort v64, v[8:9], off offset:1024
	global_load_ushort v63, v[8:9], off offset:1280
	s_waitcnt vmcnt(19)
	v_lshlrev_b32_e32 v85, 16, v85
	v_lshl_add_u64 v[8:9], v[16:17], 0, s[10:11]
	v_add_co_u32_e32 v16, vcc, s94, v16
	s_waitcnt vmcnt(18)
	v_lshlrev_b32_e32 v84, 16, v84
	s_nop 0
	v_addc_co_u32_e32 v17, vcc, 0, v17, vcc
	global_load_ushort v62, v[16:17], off offset:1024
	global_load_ushort v61, v[16:17], off offset:1280
	s_waitcnt vmcnt(19)
	v_lshlrev_b32_e32 v83, 16, v83
	v_lshl_add_u64 v[16:17], v[8:9], 0, s[10:11]
	v_add_co_u32_e32 v8, vcc, s94, v8
	s_waitcnt vmcnt(18)
	v_lshlrev_b32_e32 v82, 16, v82
	s_nop 0
	v_addc_co_u32_e32 v9, vcc, 0, v9, vcc
	global_load_ushort v60, v[8:9], off offset:1024
	global_load_ushort v59, v[8:9], off offset:1280
	s_waitcnt vmcnt(19)
	v_lshlrev_b32_e32 v81, 16, v81
	v_lshl_add_u64 v[8:9], v[16:17], 0, s[10:11]
	v_add_co_u32_e32 v16, vcc, s94, v16
	s_waitcnt vmcnt(18)
	v_lshlrev_b32_e32 v80, 16, v80
	s_nop 0
	v_addc_co_u32_e32 v17, vcc, 0, v17, vcc
	global_load_ushort v58, v[16:17], off offset:1024
	global_load_ushort v57, v[16:17], off offset:1280
	s_waitcnt vmcnt(19)
	v_lshlrev_b32_e32 v79, 16, v79
	v_lshl_add_u64 v[16:17], v[8:9], 0, s[10:11]
	v_add_co_u32_e32 v8, vcc, s94, v8
	s_waitcnt vmcnt(18)
	v_lshlrev_b32_e32 v78, 16, v78
	s_nop 0
	v_addc_co_u32_e32 v9, vcc, 0, v9, vcc
	global_load_ushort v56, v[8:9], off offset:1024
	global_load_ushort v55, v[8:9], off offset:1280
	s_waitcnt vmcnt(19)
	v_lshlrev_b32_e32 v77, 16, v77
	v_lshl_add_u64 v[8:9], v[16:17], 0, s[10:11]
	v_add_co_u32_e32 v16, vcc, s94, v16
	s_waitcnt vmcnt(18)
	v_lshlrev_b32_e32 v73, 16, v73
	s_nop 0
	v_addc_co_u32_e32 v17, vcc, 0, v17, vcc
	global_load_ushort v54, v[16:17], off offset:1024
	global_load_ushort v53, v[16:17], off offset:1280
	v_or_b32_e32 v16, s2, v89
	v_and_b32_e32 v8, 0xffffffc0, v15
	v_ashrrev_i32_e32 v9, 31, v8
	v_mad_i64_i32 v[16:17], s[10:11], v16, s93, v[4:5]
	v_lshlrev_b64 v[8:9], 1, v[8:9]
	v_lshl_add_u64 v[20:21], v[16:17], 0, v[8:9]
	v_and_b32_e32 v16, 0x70, v88
	v_mov_b32_e32 v17, v2
	v_lshl_add_u64 v[20:21], v[20:21], 0, v[16:17]
	v_add_co_u32_e32 v20, vcc, s94, v20
	s_waitcnt vmcnt(19)
	v_lshlrev_b32_e32 v72, 16, v72
	s_nop 0
	v_addc_co_u32_e32 v21, vcc, 0, v21, vcc
	global_load_dwordx4 v[90:93], v[20:21], off offset:1536
	v_or_b32_e32 v20, s2, v122
	v_mad_i64_i32 v[20:21], s[10:11], v20, s93, v[4:5]
	v_lshl_add_u64 v[20:21], v[20:21], 0, v[8:9]
	v_lshl_add_u64 v[20:21], v[20:21], 0, v[16:17]
	v_add_co_u32_e32 v20, vcc, s94, v20
	s_waitcnt vmcnt(19)
	v_lshlrev_b32_e32 v71, 16, v71
	s_nop 0
	v_addc_co_u32_e32 v21, vcc, 0, v21, vcc
	global_load_dwordx4 v[94:97], v[20:21], off offset:1536
	v_or_b32_e32 v20, s2, v123
	v_mad_i64_i32 v[20:21], s[10:11], v20, s93, v[4:5]
	v_lshl_add_u64 v[20:21], v[20:21], 0, v[8:9]
	v_lshl_add_u64 v[20:21], v[20:21], 0, v[16:17]
	v_add_co_u32_e32 v20, vcc, s94, v20
	s_waitcnt vmcnt(19)
	v_lshlrev_b32_e32 v70, 16, v70
	s_nop 0
	v_addc_co_u32_e32 v21, vcc, 0, v21, vcc
	global_load_dwordx4 v[98:101], v[20:21], off offset:1536
	v_or_b32_e32 v20, s2, v124
	v_mad_i64_i32 v[20:21], s[10:11], v20, s93, v[4:5]
	v_lshl_add_u64 v[20:21], v[20:21], 0, v[8:9]
	v_lshl_add_u64 v[20:21], v[20:21], 0, v[16:17]
	v_add_co_u32_e32 v20, vcc, s94, v20
	v_lshlrev_b32_e32 v17, 7, v1
	s_nop 0
	v_addc_co_u32_e32 v21, vcc, 0, v21, vcc
	global_load_dwordx4 v[102:105], v[20:21], off offset:1536
	v_lshl_add_u32 v20, s3, 9, v17
	v_or_b32_e32 v20, s8, v20
	v_ashrrev_i32_e32 v21, 31, v20
	v_readlane_b32 s8, v249, 50
	v_lshlrev_b64 v[20:21], 13, v[20:21]
	v_readlane_b32 s9, v249, 51
	v_readlane_b32 s10, v249, 48
	v_readlane_b32 s11, v249, 49
	v_lshl_add_u64 v[20:21], s[8:9], 0, v[20:21]
	s_lshl_b64 s[8:9], s[44:45], 14
	v_lshl_add_u64 v[20:21], v[20:21], 0, v[22:23]
	s_add_u32 s8, s10, s8
	global_load_dwordx4 v[48:51], v[20:21], off nt
	global_load_dwordx4 v[44:47], v[20:21], off offset:1024 nt
	global_load_dwordx4 v[40:43], v[20:21], off offset:2048 nt
	global_load_dwordx4 v[36:39], v[20:21], off offset:3072 nt
	v_add_co_u32_e32 v20, vcc, s94, v20
	s_addc_u32 s9, s11, s9
	s_nop 0
	v_addc_co_u32_e32 v21, vcc, 0, v21, vcc
	v_lshl_add_u64 v[106:107], v[118:119], 2, s[8:9]
	global_load_dwordx4 v[32:35], v[20:21], off nt
	global_load_dwordx4 v[28:31], v[20:21], off offset:1024 nt
	global_load_dwordx4 v[24:27], v[20:21], off offset:2048 nt
	s_nop 0
	global_load_dwordx4 v[20:23], v[20:21], off offset:3072 nt
	v_lshl_add_u64 v[110:111], v[110:111], 2, s[8:9]
	global_load_dwordx4 v[106:109], v[106:107], off nt
	v_add_u32_e32 v118, 0xc00, v118
	global_load_dwordx4 v[110:113], v[110:111], off nt
	v_lshl_add_u64 v[114:115], v[114:115], 2, s[8:9]
	v_ashrrev_i32_e32 v119, 31, v118
	global_load_dwordx4 v[114:117], v[114:115], off nt
	v_lshl_add_u64 v[118:119], v[118:119], 2, s[8:9]
	global_load_dwordx4 v[118:121], v[118:119], off nt
	v_or_b32_e32 v16, v12, v16
	v_mad_u32_u24 v89, v89, s0, v16
	s_waitcnt lgkmcnt(0)
	s_barrier
	s_waitcnt vmcnt(0)
	s_movk_i32 s3, 0x60
	v_lshlrev_b32_e32 v69, 16, v69
	v_lshlrev_b32_e32 v68, 16, v68
	v_lshlrev_b32_e32 v67, 16, v67
	v_lshlrev_b32_e32 v66, 16, v66
	v_lshlrev_b32_e32 v65, 16, v65
	v_lshlrev_b32_e32 v64, 16, v64
	v_lshlrev_b32_e32 v63, 16, v63
	v_lshlrev_b32_e32 v62, 16, v62
	v_lshlrev_b32_e32 v61, 16, v61
	v_lshlrev_b32_e32 v60, 16, v60
	v_lshlrev_b32_e32 v59, 16, v59
	ds_write_b128 v89, v[90:93] offset:34816
	v_mad_u32_u24 v89, v122, s0, v16
	v_lshlrev_b32_e32 v58, 16, v58
	v_lshlrev_b32_e32 v57, 16, v57
	v_lshlrev_b32_e32 v56, 16, v56
	v_lshlrev_b32_e32 v55, 16, v55
	v_bfe_u32 v52, v15, 4, 2
	v_and_b32_e32 v7, 15, v15
	s_mov_b64 s[8:9], 0x1800
	s_mov_b64 s[10:11], 0x15a0600
	s_add_i32 s44, s44, s26
	ds_write_b128 v89, v[94:97] offset:34816
	v_mad_u32_u24 v89, v123, s0, v16
	v_mad_u32_u24 v16, v124, s0, v16
	s_cmpk_lt_i32 s44, 0x200
	s_mov_b32 s40, s74
	ds_write_b128 v89, v[98:101] offset:34816
	ds_write_b128 v16, v[102:105] offset:34816
	ds_write_b128 v88, v[106:109]
	ds_write_b128 v88, v[110:113] offset:4096
	ds_write_b128 v88, v[114:117] offset:8192
	ds_write_b128 v88, v[118:121] offset:12288
	v_lshl_or_b32 v16, v19, 2, v17
	v_and_b32_e32 v17, 0x200, v88
	v_add_u32_e32 v17, v16, v17
	s_waitcnt lgkmcnt(0)
	s_barrier
	ds_read_b32 v17, v17
	v_cvt_pk_bf16_f32 v48, v48, v49
	v_cvt_pk_bf16_f32 v49, v50, v51
	v_cvt_pk_bf16_f32 v44, v44, v45
	v_cvt_pk_bf16_f32 v45, v46, v47
	s_waitcnt lgkmcnt(0)
	v_mul_f32_e32 v88, 0x3fb8aa3b, v17
	v_mul_f32_e32 v17, 0xbfb8aa3b, v17
	v_exp_f32_e32 v17, v17
	v_exp_f32_e32 v88, v88
	v_cvt_pk_bf16_f32 v40, v40, v41
	v_cvt_pk_bf16_f32 v41, v42, v43
	v_mul_f32_e32 v17, v17, v86
	v_mul_f32_e32 v87, v88, v87
	v_lshl_or_b32 v88, v3, 1, v0
	v_cvt_pk_bf16_f32 v17, v17, s0
	ds_write_b16 v88, v17 offset:26624
	v_lshlrev_b32_e32 v17, 4, v74
	v_and_b32_e32 v17, 0x600, v17
	v_add_u32_e32 v17, v16, v17
	ds_read_b32 v17, v17
	v_mul_f32_e32 v87, 0x3e3504f3, v87
	v_cvt_pk_bf16_f32 v87, v87, s0
	ds_write_b16 v88, v87 offset:18432
	v_cvt_pk_bf16_f32 v36, v36, v37
	s_waitcnt lgkmcnt(1)
	v_mul_f32_e32 v86, 0x3fb8aa3b, v17
	v_mul_f32_e32 v17, 0xbfb8aa3b, v17
	v_exp_f32_e32 v86, v86
	v_exp_f32_e32 v17, v17
	v_cvt_pk_bf16_f32 v37, v38, v39
	v_cvt_pk_bf16_f32 v32, v32, v33
	v_mul_f32_e32 v85, v86, v85
	v_and_or_b32 v86, v74, s3, v19
	v_mul_f32_e32 v17, v17, v84
	v_lshl_or_b32 v86, v86, 1, v0
	v_cvt_pk_bf16_f32 v17, v17, s0
	ds_write_b16 v86, v17 offset:26624
	v_lshlrev_b32_e32 v17, 4, v75
	v_and_b32_e32 v17, 0xa00, v17
	v_add_u32_e32 v17, v16, v17
	ds_read_b32 v17, v17
	s_movk_i32 s3, 0xa0
	v_mul_f32_e32 v85, 0x3e3504f3, v85
	v_cvt_pk_bf16_f32 v85, v85, s0
	ds_write_b16 v86, v85 offset:18432
	s_waitcnt lgkmcnt(1)
	v_mul_f32_e32 v84, 0x3fb8aa3b, v17
	v_mul_f32_e32 v17, 0xbfb8aa3b, v17
	v_exp_f32_e32 v84, v84
	v_exp_f32_e32 v17, v17
	v_cvt_pk_bf16_f32 v33, v34, v35
	v_cvt_pk_bf16_f32 v28, v28, v29
	v_mul_f32_e32 v83, v84, v83
	v_and_or_b32 v84, v75, s3, v19
	v_mul_f32_e32 v17, v17, v82
	v_lshl_or_b32 v84, v84, 1, v0
	v_cvt_pk_bf16_f32 v17, v17, s0
	ds_write_b16 v84, v17 offset:26624
	v_lshlrev_b32_e32 v17, 4, v76
	v_and_b32_e32 v17, 0xe00, v17
	v_add_u32_e32 v17, v16, v17
	ds_read_b32 v17, v17
	s_movk_i32 s3, 0xe0
	v_mul_f32_e32 v83, 0x3e3504f3, v83
	v_cvt_pk_bf16_f32 v83, v83, s0
	ds_write_b16 v84, v83 offset:18432
	s_waitcnt lgkmcnt(1)
	v_mul_f32_e32 v82, 0x3fb8aa3b, v17
	v_mul_f32_e32 v17, 0xbfb8aa3b, v17
	v_exp_f32_e32 v82, v82
	v_exp_f32_e32 v17, v17
	v_cvt_pk_bf16_f32 v29, v30, v31
	v_cvt_pk_bf16_f32 v24, v24, v25
	v_mul_f32_e32 v81, v82, v81
	v_and_or_b32 v82, v76, s3, v19
	v_mul_f32_e32 v17, v17, v80
	v_lshl_or_b32 v82, v82, 1, v0
	v_cvt_pk_bf16_f32 v17, v17, s0
	v_or_b32_e32 v80, 0x100, v3
	ds_write_b16 v82, v17 offset:26624
	v_lshlrev_b32_e32 v17, 4, v80
	v_and_b32_e32 v17, 0x1200, v17
	v_add_u32_e32 v17, v16, v17
	ds_read_b32 v17, v17
	v_mul_f32_e32 v81, 0x3e3504f3, v81
	v_cvt_pk_bf16_f32 v81, v81, s0
	ds_write_b16 v82, v81 offset:18432
	s_movk_i32 s3, 0x120
	s_waitcnt lgkmcnt(1)
	v_mul_f32_e32 v81, 0x3fb8aa3b, v17
	v_mul_f32_e32 v17, 0xbfb8aa3b, v17
	v_exp_f32_e32 v81, v81
	v_exp_f32_e32 v17, v17
	v_cvt_pk_bf16_f32 v25, v26, v27
	v_cvt_pk_bf16_f32 v20, v20, v21
	v_mul_f32_e32 v79, v81, v79
	v_and_or_b32 v81, v80, s3, v19
	v_mul_f32_e32 v17, v17, v78
	v_lshl_or_b32 v81, v81, 1, v0
	v_cvt_pk_bf16_f32 v17, v17, s0
	v_or_b32_e32 v78, 0x140, v3
	ds_write_b16 v81, v17 offset:26624
	v_lshlrev_b32_e32 v17, 4, v78
	v_and_b32_e32 v17, 0x1600, v17
	v_add_u32_e32 v17, v16, v17
	ds_read_b32 v17, v17
	v_mul_f32_e32 v79, 0x3e3504f3, v79
	v_cvt_pk_bf16_f32 v79, v79, s0
	ds_write_b16 v81, v79 offset:18432
	s_movk_i32 s3, 0x160
	s_waitcnt lgkmcnt(1)
	v_mul_f32_e32 v79, 0x3fb8aa3b, v17
	v_mul_f32_e32 v17, 0xbfb8aa3b, v17
	v_exp_f32_e32 v79, v79
	v_exp_f32_e32 v17, v17
	v_cvt_pk_bf16_f32 v21, v22, v23
	v_mul_f32_e32 v77, v79, v77
	v_and_or_b32 v79, v78, s3, v19
	v_mul_f32_e32 v17, v17, v73
	v_lshl_or_b32 v79, v79, 1, v0
	v_cvt_pk_bf16_f32 v17, v17, s0
	v_or_b32_e32 v73, 0x180, v3
	ds_write_b16 v79, v17 offset:26624
	v_lshlrev_b32_e32 v17, 4, v73
	v_and_b32_e32 v17, 0x1a00, v17
	v_add_u32_e32 v17, v16, v17
	ds_read_b32 v17, v17
	v_mul_f32_e32 v77, 0x3e3504f3, v77
	v_cvt_pk_bf16_f32 v77, v77, s0
	ds_write_b16 v79, v77 offset:18432
	s_movk_i32 s3, 0x1a0
	s_waitcnt lgkmcnt(1)
	v_mul_f32_e32 v77, 0x3fb8aa3b, v17
	v_mul_f32_e32 v17, 0xbfb8aa3b, v17
	v_exp_f32_e32 v77, v77
	v_exp_f32_e32 v17, v17
	v_mul_f32_e32 v72, v77, v72
	v_and_or_b32 v77, v73, s3, v19
	v_mul_f32_e32 v17, v17, v71
	v_lshl_or_b32 v77, v77, 1, v0
	v_cvt_pk_bf16_f32 v17, v17, s0
	v_or_b32_e32 v71, 0x1c0, v3
	ds_write_b16 v77, v17 offset:26624
	v_lshlrev_b32_e32 v17, 4, v71
	v_and_b32_e32 v17, 0x1e00, v17
	v_add_u32_e32 v17, v16, v17
	ds_read_b32 v17, v17
	v_mul_f32_e32 v72, 0x3e3504f3, v72
	v_cvt_pk_bf16_f32 v72, v72, s0
	ds_write_b16 v77, v72 offset:18432
	s_movk_i32 s3, 0x1e0
	s_waitcnt lgkmcnt(1)
	v_mul_f32_e32 v72, 0x3fb8aa3b, v17
	v_mul_f32_e32 v17, 0xbfb8aa3b, v17
	v_exp_f32_e32 v72, v72
	v_exp_f32_e32 v17, v17
	v_mul_f32_e32 v70, v72, v70
	v_and_or_b32 v72, v71, s3, v19
	v_mul_f32_e32 v17, v17, v69
	v_lshl_or_b32 v72, v72, 1, v0
	v_cvt_pk_bf16_f32 v17, v17, s0
	ds_write_b16 v72, v17 offset:26624
	v_or_b32_e32 v17, 0x200, v3
	v_lshlrev_b32_e32 v69, 4, v17
	v_and_b32_e32 v69, 0x2200, v69
	v_add_u32_e32 v69, v16, v69
	ds_read_b32 v69, v69
	v_mul_f32_e32 v70, 0x3e3504f3, v70
	v_cvt_pk_bf16_f32 v70, v70, s0
	ds_write_b16 v72, v70 offset:18432
	s_movk_i32 s3, 0x220
	s_waitcnt lgkmcnt(1)
	v_mul_f32_e32 v70, 0x3fb8aa3b, v69
	v_exp_f32_e32 v70, v70
	v_and_or_b32 v17, v17, s3, v19
	v_lshl_or_b32 v17, v17, 1, v0
	s_movk_i32 s3, 0x260
	v_mul_f32_e32 v68, v70, v68
	v_mul_f32_e32 v68, 0x3e3504f3, v68
	v_cvt_pk_bf16_f32 v68, v68, s0
	ds_write_b16 v17, v68 offset:18432
	v_mul_f32_e32 v68, 0xbfb8aa3b, v69
	v_exp_f32_e32 v68, v68
	s_nop 0
	v_mul_f32_e32 v67, v68, v67
	v_cvt_pk_bf16_f32 v67, v67, s0
	ds_write_b16 v17, v67 offset:26624
	v_or_b32_e32 v17, 0x240, v3
	v_lshlrev_b32_e32 v67, 4, v17
	v_and_b32_e32 v67, 0x2600, v67
	v_add_u32_e32 v67, v16, v67
	ds_read_b32 v67, v67
	v_and_or_b32 v17, v17, s3, v19
	v_lshl_or_b32 v17, v17, 1, v0
	s_movk_i32 s3, 0x2a0
	s_waitcnt lgkmcnt(0)
	v_mul_f32_e32 v68, 0x3fb8aa3b, v67
	v_exp_f32_e32 v68, v68
	s_nop 0
	v_mul_f32_e32 v66, v68, v66
	v_mul_f32_e32 v66, 0x3e3504f3, v66
	v_cvt_pk_bf16_f32 v66, v66, s0
	ds_write_b16 v17, v66 offset:18432
	v_mul_f32_e32 v66, 0xbfb8aa3b, v67
	v_exp_f32_e32 v66, v66
	s_nop 0
	v_mul_f32_e32 v65, v66, v65
	v_cvt_pk_bf16_f32 v65, v65, s0
	ds_write_b16 v17, v65 offset:26624
	v_or_b32_e32 v17, 0x280, v3
	v_lshlrev_b32_e32 v65, 4, v17
	v_and_b32_e32 v65, 0x2a00, v65
	v_add_u32_e32 v65, v16, v65
	ds_read_b32 v65, v65
	v_and_or_b32 v17, v17, s3, v19
	v_lshl_or_b32 v17, v17, 1, v0
	s_movk_i32 s3, 0x2e0
	s_waitcnt lgkmcnt(0)
	v_mul_f32_e32 v66, 0x3fb8aa3b, v65
	v_exp_f32_e32 v66, v66
	s_nop 0
	v_mul_f32_e32 v64, v66, v64
	v_mul_f32_e32 v64, 0x3e3504f3, v64
	v_cvt_pk_bf16_f32 v64, v64, s0
	ds_write_b16 v17, v64 offset:18432
	v_mul_f32_e32 v64, 0xbfb8aa3b, v65
	v_exp_f32_e32 v64, v64
	s_nop 0
	v_mul_f32_e32 v63, v64, v63
	v_cvt_pk_bf16_f32 v63, v63, s0
	ds_write_b16 v17, v63 offset:26624
	v_or_b32_e32 v17, 0x2c0, v3
	v_lshlrev_b32_e32 v63, 4, v17
	v_and_b32_e32 v63, 0x2e00, v63
	v_add_u32_e32 v63, v16, v63
	ds_read_b32 v63, v63
	v_and_or_b32 v17, v17, s3, v19
	v_lshl_or_b32 v17, v17, 1, v0
	s_movk_i32 s3, 0x320
	s_waitcnt lgkmcnt(0)
	v_mul_f32_e32 v64, 0x3fb8aa3b, v63
	v_exp_f32_e32 v64, v64
	s_nop 0
	v_mul_f32_e32 v62, v64, v62
	v_mul_f32_e32 v62, 0x3e3504f3, v62
	v_cvt_pk_bf16_f32 v62, v62, s0
	ds_write_b16 v17, v62 offset:18432
	v_mul_f32_e32 v62, 0xbfb8aa3b, v63
	v_exp_f32_e32 v62, v62
	s_nop 0
	v_mul_f32_e32 v61, v62, v61
	v_cvt_pk_bf16_f32 v61, v61, s0
	ds_write_b16 v17, v61 offset:26624
	v_or_b32_e32 v17, 0x300, v3
	v_lshlrev_b32_e32 v61, 4, v17
	v_and_b32_e32 v61, 0x3200, v61
	v_add_u32_e32 v61, v16, v61
	ds_read_b32 v61, v61
	v_and_or_b32 v17, v17, s3, v19
	v_lshl_or_b32 v17, v17, 1, v0
	s_movk_i32 s3, 0x360
	s_waitcnt lgkmcnt(0)
	v_mul_f32_e32 v62, 0x3fb8aa3b, v61
	v_exp_f32_e32 v62, v62
	s_nop 0
	v_mul_f32_e32 v60, v62, v60
	v_mul_f32_e32 v60, 0x3e3504f3, v60
	v_cvt_pk_bf16_f32 v60, v60, s0
	ds_write_b16 v17, v60 offset:18432
	v_mul_f32_e32 v60, 0xbfb8aa3b, v61
	v_exp_f32_e32 v60, v60
	s_nop 0
	v_mul_f32_e32 v59, v60, v59
	v_cvt_pk_bf16_f32 v59, v59, s0
	ds_write_b16 v17, v59 offset:26624
	v_or_b32_e32 v17, 0x340, v3
	v_lshlrev_b32_e32 v59, 4, v17
	v_and_b32_e32 v59, 0x3600, v59
	v_add_u32_e32 v59, v16, v59
	ds_read_b32 v59, v59
	v_and_or_b32 v17, v17, s3, v19
	v_lshl_or_b32 v17, v17, 1, v0
	s_movk_i32 s3, 0x3a0
	s_waitcnt lgkmcnt(0)
	v_mul_f32_e32 v60, 0x3fb8aa3b, v59
	v_exp_f32_e32 v60, v60
	s_nop 0
	v_mul_f32_e32 v58, v60, v58
	v_mul_f32_e32 v58, 0x3e3504f3, v58
	v_cvt_pk_bf16_f32 v58, v58, s0
	ds_write_b16 v17, v58 offset:18432
	v_mul_f32_e32 v58, 0xbfb8aa3b, v59
	v_exp_f32_e32 v58, v58
	s_nop 0
	v_mul_f32_e32 v57, v58, v57
	v_cvt_pk_bf16_f32 v57, v57, s0
	ds_write_b16 v17, v57 offset:26624
	v_or_b32_e32 v17, 0x380, v3
	v_lshlrev_b32_e32 v57, 4, v17
	v_and_b32_e32 v57, 0x3a00, v57
	v_add_u32_e32 v57, v16, v57
	ds_read_b32 v57, v57
	v_and_or_b32 v17, v17, s3, v19
	v_lshl_or_b32 v17, v17, 1, v0
	v_or_b32_e32 v3, 0x3c0, v3
	s_movk_i32 s3, 0x3e0
	s_waitcnt lgkmcnt(0)
	v_mul_f32_e32 v58, 0x3fb8aa3b, v57
	v_exp_f32_e32 v58, v58
	s_nop 0
	v_mul_f32_e32 v56, v58, v56
	v_mul_f32_e32 v56, 0x3e3504f3, v56
	v_cvt_pk_bf16_f32 v56, v56, s0
	ds_write_b16 v17, v56 offset:18432
	v_mul_f32_e32 v56, 0xbfb8aa3b, v57
	v_exp_f32_e32 v56, v56
	s_nop 0
	v_mul_f32_e32 v55, v56, v55
	v_cvt_pk_bf16_f32 v55, v55, s0
	ds_write_b16 v17, v55 offset:26624
	v_lshlrev_b32_e32 v17, 4, v3
	v_and_b32_e32 v17, 0x3e00, v17
	v_add_u32_e32 v16, v16, v17
	ds_read_b32 v16, v16
	v_lshlrev_b32_e32 v17, 16, v54
	v_and_or_b32 v3, v3, s3, v19
	v_lshl_or_b32 v3, v3, 1, v0
	s_movk_i32 s3, 0x1200
	s_waitcnt lgkmcnt(0)
	v_mul_f32_e32 v54, 0x3fb8aa3b, v16
	v_exp_f32_e32 v54, v54
	v_mul_f32_e32 v16, 0xbfb8aa3b, v16
	v_exp_f32_e32 v16, v16
	v_and_b32_e32 v19, 48, v15
	v_mul_f32_e32 v17, v54, v17
	v_mul_f32_e32 v17, 0x3e3504f3, v17
	v_cvt_pk_bf16_f32 v17, v17, s0
	ds_write_b16 v3, v17 offset:18432
	v_lshlrev_b32_e32 v17, 16, v53
	v_mul_f32_e32 v16, v16, v17
	v_mul_lo_u32 v17, v1, s3
	s_movk_i32 s3, 0x78
	v_cvt_pk_bf16_f32 v16, v16, s0
	v_and_or_b32 v1, v13, s3, v17
	ds_write_b16 v3, v16 offset:26624
	v_mad_u32_u24 v3, v52, s0, v1
	s_waitcnt lgkmcnt(0)
	s_barrier
	ds_write_b64 v3, v[48:49]
	v_lshrrev_b32_e32 v3, 4, v74
	v_mad_u32_u24 v3, v3, s0, v1
	ds_write_b64 v3, v[44:45]
	v_lshrrev_b32_e32 v3, 4, v75
	v_mad_u32_u24 v3, v3, s0, v1
	ds_write_b64 v3, v[40:41]
	v_lshrrev_b32_e32 v3, 4, v76
	v_mad_u32_u24 v3, v3, s0, v1
	ds_write_b64 v3, v[36:37]
	v_lshrrev_b32_e32 v3, 4, v80
	v_mad_u32_u24 v3, v3, s0, v1
	ds_write_b64 v3, v[32:33]
	v_lshrrev_b32_e32 v3, 4, v78
	v_mad_u32_u24 v3, v3, s0, v1
	ds_write_b64 v3, v[28:29]
	v_lshrrev_b32_e32 v3, 4, v73
	v_mad_u32_u24 v3, v3, s0, v1
	ds_write_b64 v3, v[24:25]
	v_lshrrev_b32_e32 v3, 4, v71
	v_mad_u32_u24 v1, v3, s0, v1
	ds_write_b64 v1, v[20:21]
	v_lshlrev_b32_e32 v1, 6, v7
	v_or3_b32 v0, v0, v19, v1
	s_waitcnt lgkmcnt(0)
	s_barrier
	ds_read_b128 v[20:23], v0 offset:18432
	ds_read_b128 v[24:27], v0 offset:26624
	ds_read_b128 v[36:39], v0 offset:19456
	ds_read_b128 v[30:33], v0 offset:27648
	s_waitcnt lgkmcnt(2)
	v_mfma_f32_16x16x32_bf16 v[40:43], v[24:27], v[20:23], 0
	v_lshlrev_b32_e32 v28, 2, v52
	v_cmp_lt_u32_e64 s[38:39], v28, v7
	v_or_b32_e32 v1, 2, v28
	s_waitcnt lgkmcnt(0)
	v_mfma_f32_16x16x32_bf16 v[30:33], v[30:33], v[36:39], 0
	s_nop 2
	v_cndmask_b32_e64 v3, 0, v41, s[38:39]
	v_cmp_le_u32_e64 s[38:39], v1, v7
	v_cmp_gt_u32_e32 vcc, v28, v7
	v_mfma_f32_16x16x32_bf16 v[24:27], v[24:27], v[36:39], 0
	v_cndmask_b32_e64 v1, 0, v42, s[38:39]
	v_or_b32_e32 v29, 3, v28
	v_or_b32_e32 v35, 17, v28
	v_or_b32_e32 v42, 16, v7
	v_cndmask_b32_e64 v0, v40, 0, vcc
	v_cmp_le_u32_e64 s[38:39], v29, v7
	v_or_b32_e32 v40, 18, v28
	v_cndmask_b32_e64 v29, v30, 0, vcc
	v_cmp_le_u32_e32 vcc, v35, v42
	v_bfe_u32 v15, v15, 2, 2
	v_lshlrev_b32_e32 v16, 3, v52
	v_or_b32_e32 v41, 19, v28
	v_cndmask_b32_e32 v30, 0, v31, vcc
	v_cmp_le_u32_e32 vcc, v40, v42
	v_cvt_pk_bf16_f32 v56, v24, v25
	v_or_b32_e32 v24, v28, v15
	v_cndmask_b32_e32 v31, 0, v32, vcc
	v_cmp_le_u32_e32 vcc, v41, v42
	v_mul_u32_u24_e32 v24, 0x90, v24
	v_and_b32_e32 v13, 24, v13
	v_or_b32_e32 v15, v16, v15
	v_cndmask_b32_e64 v34, 0, v43, s[38:39]
	v_cndmask_b32_e32 v32, 0, v33, vcc
	v_add3_u32 v12, v12, v24, v13
	v_mul_u32_u24_e32 v15, 0x90, v15
	v_cvt_pk_bf16_f32 v1, v1, v34
	v_cvt_pk_bf16_f32 v0, v0, v3
	v_mov_b32_e32 v3, v2
	v_cvt_pk_bf16_f32 v57, v26, v27
	v_cvt_pk_bf16_f32 v58, v29, v30
	v_cvt_pk_bf16_f32 v59, v31, v32
	v_add3_u32 v13, v17, v15, v13
	ds_read_b64_tr_b16 v[26:27], v12 offset:37120
	ds_read_b64_tr_b16 v[24:25], v12 offset:34816
	ds_read_b64_tr_b16 v[28:29], v12 offset:34848
	ds_read_b64_tr_b16 v[32:33], v13 offset:576
	ds_read_b64_tr_b16 v[30:31], v13
	ds_read_b64_tr_b16 v[40:41], v13 offset:32
	s_waitcnt lgkmcnt(4)
	v_mfma_f32_16x16x32_bf16 v[42:45], v[24:27], v[0:3], 0
	v_mov_b32_e32 v17, v2
	v_mfma_f32_16x16x32_bf16 v[24:27], v[24:27], v[56:59], 0
	s_waitcnt lgkmcnt(1)
	v_mfma_f32_16x16x32_bf16 v[52:55], v[30:33], v[20:23], v[42:45]
	v_mfma_f32_16x16x32_bf16 v[32:35], v[30:33], v[36:39], v[24:27]
	ds_read_b64_tr_b16 v[30:31], v12 offset:37152
	s_nop 1
	ds_read_b64_tr_b16 v[42:43], v13 offset:608
	s_waitcnt lgkmcnt(1)
	v_mfma_f32_16x16x32_bf16 v[24:27], v[28:31], v[0:3], 0
	s_nop 1
	v_mul_f32_e64 v80, v32, v32
	v_mul_f32_e64 v81, v33, v33
	s_waitcnt lgkmcnt(0)
	v_mfma_f32_16x16x32_bf16 v[48:51], v[40:43], v[20:23], v[24:27]
	v_mfma_f32_16x16x32_bf16 v[24:27], v[28:31], v[56:59], 0
	v_mfma_f32_16x16x32_bf16 v[28:31], v[40:43], v[36:39], v[24:27]
	s_nop 6
	ds_read_b64_tr_b16 v[24:25], v12 offset:34880
	ds_read_b64_tr_b16 v[26:27], v12 offset:37184
	ds_read_b64_tr_b16 v[40:41], v13 offset:64
	ds_read_b64_tr_b16 v[42:43], v13 offset:640
	ds_read_b64_tr_b16 v[60:61], v12 offset:34912
	ds_read_b64_tr_b16 v[62:63], v12 offset:37216
	ds_read_b64_tr_b16 v[64:65], v13 offset:96
	ds_read_b64_tr_b16 v[66:67], v13 offset:672
	v_pk_mul_f32 v[12:13], v[54:55], v[54:55]
	s_waitcnt lgkmcnt(6)
	v_mfma_f32_16x16x32_bf16 v[44:47], v[24:27], v[0:3], 0
	v_mfma_f32_16x16x32_bf16 v[24:27], v[24:27], v[56:59], 0
	s_waitcnt lgkmcnt(4)
	v_mfma_f32_16x16x32_bf16 v[44:47], v[40:43], v[20:23], v[44:47]
	v_mfma_f32_16x16x32_bf16 v[24:27], v[40:43], v[36:39], v[24:27]
	s_waitcnt lgkmcnt(2)
	v_mfma_f32_16x16x32_bf16 v[40:43], v[60:63], v[0:3], 0
	v_or_b32_e32 v0, s2, v7
	s_waitcnt lgkmcnt(0)
	v_mfma_f32_16x16x32_bf16 v[40:43], v[64:67], v[20:23], v[40:43]
	v_mfma_f32_16x16x32_bf16 v[20:23], v[60:63], v[56:59], 0
	v_mfma_f32_16x16x32_bf16 v[20:23], v[64:67], v[36:39], v[20:23]
	v_mul_f32_e64 v36, v52, v52
	v_mul_f32_e64 v37, v53, v53
	s_nop 3
	v_mul_f32_e32 v1, v40, v40
	v_pk_mov_b32 v[38:39], v[36:37], v[12:13] op_sel:[1,0]
	v_mov_b32_e32 v37, v13
	v_pk_add_f32 v[12:13], v[38:39], v[36:37]
	v_pk_mul_f32 v[36:37], v[50:51], v[50:51]
	v_pk_mul_f32 v[38:39], v[48:49], v[48:49]
	v_mul_f32_e32 v3, v41, v41
	v_pk_mov_b32 v[56:57], v[38:39], v[36:37] op_sel:[1,0]
	v_mov_b32_e32 v39, v37
	v_pk_add_f32 v[36:37], v[56:57], v[38:39]
	v_pk_add_f32 v[12:13], v[12:13], v[12:13] op_sel:[0,1] op_sel_hi:[1,0]
	v_pk_add_f32 v[36:37], v[36:37], v[36:37] op_sel:[0,1] op_sel_hi:[1,0]
	v_mov_b32_e32 v13, v1
	v_mov_b32_e32 v37, v3
	v_pk_add_f32 v[12:13], v[12:13], v[36:37]
	v_mul_f32_e32 v36, v45, v45
	v_mul_f32_e32 v38, v47, v47
	v_mul_f32_e32 v7, v42, v42
	v_mul_f32_e32 v15, v43, v43
	v_pk_fma_f32 v[36:37], v[44:45], v[44:45], v[36:37] op_sel_hi:[1,1,0]
	v_pk_fma_f32 v[38:39], v[46:47], v[46:47], v[38:39] op_sel_hi:[1,1,0]
	v_mov_b32_e32 v37, v7
	v_mov_b32_e32 v39, v15
	v_pk_add_f32 v[36:37], v[36:37], v[38:39]
	s_nop 0
	v_pk_add_f32 v[12:13], v[12:13], v[36:37]
	v_mad_i64_i32 v[36:37], s[2:3], v0, s93, v[4:5]
	v_lshl_add_u64 v[58:59], v[36:37], 0, v[8:9]
	v_lshl_add_u64 v[58:59], v[58:59], 0, v[16:17]
	v_lshl_add_u64 v[74:75], v[58:59], 0, s[8:9]
	v_add_co_u32_e32 v58, vcc, s94, v58
	v_mov_b64_e32 v[68:69], v[138:139]
	v_mov_b64_e32 v[72:73], v[140:141]
	v_addc_co_u32_e32 v59, vcc, 0, v59, vcc
	v_mov_b64_e32 v[62:63], v[136:137]
	v_pk_add_f32 v[12:13], v[12:13], v[12:13] op_sel:[0,1] op_sel_hi:[1,0]
	s_nop 0
	v_and_b32_e32 v3, 0xffff0000, v62
	v_mov_b32_e32 v1, v12
	s_nop 1
	v_permlane16_swap_b32_e32 v12, v1
	v_add_f32_e32 v13, v12, v1
	v_ashrrev_i32_e32 v1, 31, v0
	v_lshlrev_b64 v[36:37], 11, v[0:1]
	v_lshlrev_b32_e32 v1, 16, v62
	v_mul_f32_e32 v7, 0xbfb8aa3b, v1
	v_exp_f32_e32 v58, v7
	v_mul_f32_e32 v7, 0xbfb8aa3b, v3
	v_exp_f32_e32 v59, v7
	v_lshl_add_u64 v[36:37], s[24:25], 0, v[36:37]
	v_lshl_add_u64 v[60:61], v[36:37], 0, v[8:9]
	s_nop 1
	v_mov_b64_e32 v[36:37], v[156:157]
	v_mov_b64_e32 v[38:39], v[158:159]
	v_pk_add_f32 v[58:59], v[58:59], 1.0 op_sel_hi:[1,0]
	v_mov_b32_e32 v57, v13
	v_div_scale_f32 v7, s[2:3], v59, v59, v3
	v_rcp_f32_e32 v12, v7
	v_permlane32_swap_b32_e32 v13, v57
	v_or_b32_e32 v0, 16, v0
	v_fma_f32 v15, -v7, v12, 1.0
	v_fmac_f32_e32 v12, v15, v12
	v_div_scale_f32 v15, vcc, v3, v59, v3
	v_mul_f32_e32 v56, v15, v12
	v_fma_f32 v62, -v7, v56, v15
	v_fmac_f32_e32 v56, v62, v12
	v_fma_f32 v7, -v7, v56, v15
	v_div_fmas_f32 v7, v7, v12, v56
	v_div_fixup_f32 v59, v7, v59, v3
	v_div_scale_f32 v3, s[2:3], v58, v58, v1
	v_rcp_f32_e32 v7, v3
	s_nop 0
	v_fma_f32 v12, -v3, v7, 1.0
	v_fmac_f32_e32 v7, v12, v7
	v_div_scale_f32 v12, vcc, v1, v58, v1
	v_mul_f32_e32 v15, v12, v7
	v_fma_f32 v56, -v3, v15, v12
	v_fmac_f32_e32 v15, v56, v7
	v_fma_f32 v3, -v3, v15, v12
	v_div_fmas_f32 v3, v3, v7, v15
	v_div_fixup_f32 v58, v3, v58, v1
	v_lshlrev_b32_e32 v1, 16, v63
	v_and_b32_e32 v3, 0xffff0000, v63
	v_mul_f32_e32 v7, 0xbfb8aa3b, v1
	v_exp_f32_e32 v62, v7
	v_mul_f32_e32 v7, 0xbfb8aa3b, v3
	v_exp_f32_e32 v63, v7
	s_nop 0
	v_pk_add_f32 v[62:63], v[62:63], 1.0 op_sel_hi:[1,0]
	s_nop 0
	v_div_scale_f32 v7, s[2:3], v63, v63, v3
	v_rcp_f32_e32 v12, v7
	s_nop 0
	v_fma_f32 v15, -v7, v12, 1.0
	v_fmac_f32_e32 v12, v15, v12
	v_div_scale_f32 v15, vcc, v3, v63, v3
	v_mul_f32_e32 v56, v15, v12
	v_fma_f32 v64, -v7, v56, v15
	v_fmac_f32_e32 v56, v64, v12
	v_fma_f32 v7, -v7, v56, v15
	v_div_fmas_f32 v7, v7, v12, v56
	v_div_fixup_f32 v63, v7, v63, v3
	v_div_scale_f32 v3, s[2:3], v62, v62, v1
	v_rcp_f32_e32 v7, v3
	v_lshl_add_u64 v[64:65], v[60:61], 0, v[16:17]
	v_lshl_add_u64 v[60:61], v[64:65], 0, s[10:11]
	v_fma_f32 v12, -v3, v7, 1.0
	v_fmac_f32_e32 v7, v12, v7
	v_div_scale_f32 v12, vcc, v1, v62, v1
	v_mul_f32_e32 v15, v12, v7
	v_fma_f32 v56, -v3, v15, v12
	v_fmac_f32_e32 v15, v56, v7
	v_fma_f32 v3, -v3, v15, v12
	v_div_fmas_f32 v3, v3, v7, v15
	v_div_fixup_f32 v62, v3, v62, v1
	v_lshlrev_b32_e32 v1, 16, v68
	v_and_b32_e32 v3, 0xffff0000, v68
	v_mul_f32_e32 v7, 0xbfb8aa3b, v1
	v_exp_f32_e32 v66, v7
	v_mul_f32_e32 v7, 0xbfb8aa3b, v3
	v_exp_f32_e32 v67, v7
	s_nop 0
	v_pk_add_f32 v[66:67], v[66:67], 1.0 op_sel_hi:[1,0]
	s_nop 0
	v_div_scale_f32 v7, s[2:3], v67, v67, v3
	v_rcp_f32_e32 v12, v7
	s_nop 0
	v_fma_f32 v15, -v7, v12, 1.0
	v_fmac_f32_e32 v12, v15, v12
	v_div_scale_f32 v15, vcc, v3, v67, v3
	v_mul_f32_e32 v56, v15, v12
	v_fma_f32 v68, -v7, v56, v15
	v_fmac_f32_e32 v56, v68, v12
	v_fma_f32 v7, -v7, v56, v15
	v_div_fmas_f32 v7, v7, v12, v56
	v_div_fixup_f32 v67, v7, v67, v3
	v_div_scale_f32 v3, s[2:3], v66, v66, v1
	v_rcp_f32_e32 v7, v3
	s_nop 0
	v_fma_f32 v12, -v3, v7, 1.0
	v_fmac_f32_e32 v7, v12, v7
	v_div_scale_f32 v12, vcc, v1, v66, v1
	v_mul_f32_e32 v15, v12, v7
	v_fma_f32 v56, -v3, v15, v12
	v_fmac_f32_e32 v15, v56, v7
	v_fma_f32 v3, -v3, v15, v12
	v_div_fmas_f32 v3, v3, v7, v15
	v_div_fixup_f32 v66, v3, v66, v1
	v_lshlrev_b32_e32 v1, 16, v69
	v_and_b32_e32 v3, 0xffff0000, v69
	v_mul_f32_e32 v7, 0xbfb8aa3b, v1
	v_exp_f32_e32 v68, v7
	v_mul_f32_e32 v7, 0xbfb8aa3b, v3
	v_exp_f32_e32 v69, v7
	s_nop 0
	v_pk_add_f32 v[68:69], v[68:69], 1.0 op_sel_hi:[1,0]
	s_nop 0
	v_div_scale_f32 v7, s[2:3], v69, v69, v3
	v_rcp_f32_e32 v12, v7
	s_nop 0
	v_fma_f32 v15, -v7, v12, 1.0
	v_fmac_f32_e32 v12, v15, v12
	v_div_scale_f32 v15, vcc, v3, v69, v3
	v_mul_f32_e32 v56, v15, v12
	v_fma_f32 v70, -v7, v56, v15
	v_fmac_f32_e32 v56, v70, v12
	v_fma_f32 v7, -v7, v56, v15
	v_div_fmas_f32 v7, v7, v12, v56
	v_div_fixup_f32 v69, v7, v69, v3
	v_div_scale_f32 v3, s[2:3], v68, v68, v1
	v_rcp_f32_e32 v7, v3
	s_nop 0
	v_fma_f32 v12, -v3, v7, 1.0
	v_fmac_f32_e32 v7, v12, v7
	v_div_scale_f32 v12, vcc, v1, v68, v1
	v_mul_f32_e32 v15, v12, v7
	v_fma_f32 v56, -v3, v15, v12
	v_fmac_f32_e32 v15, v56, v7
	v_fma_f32 v3, -v3, v15, v12
	v_div_fmas_f32 v3, v3, v7, v15
	v_div_fixup_f32 v68, v3, v68, v1
	v_lshlrev_b32_e32 v1, 16, v72
	v_and_b32_e32 v3, 0xffff0000, v72
	v_mul_f32_e32 v7, 0xbfb8aa3b, v1
	v_exp_f32_e32 v70, v7
	v_mul_f32_e32 v7, 0xbfb8aa3b, v3
	v_exp_f32_e32 v71, v7
	s_nop 0
	v_pk_add_f32 v[70:71], v[70:71], 1.0 op_sel_hi:[1,0]
	s_nop 0
	v_div_scale_f32 v7, s[2:3], v71, v71, v3
	v_rcp_f32_e32 v12, v7
	s_nop 0
	v_fma_f32 v15, -v7, v12, 1.0
	v_fmac_f32_e32 v12, v15, v12
	v_div_scale_f32 v15, vcc, v3, v71, v3
	v_mul_f32_e32 v56, v15, v12
	v_fma_f32 v72, -v7, v56, v15
	v_fmac_f32_e32 v56, v72, v12
	v_fma_f32 v7, -v7, v56, v15
	v_div_fmas_f32 v7, v7, v12, v56
	v_div_fixup_f32 v71, v7, v71, v3
	v_div_scale_f32 v3, s[2:3], v70, v70, v1
	v_rcp_f32_e32 v7, v3
	s_nop 0
	v_fma_f32 v12, -v3, v7, 1.0
	v_fmac_f32_e32 v7, v12, v7
	v_div_scale_f32 v12, vcc, v1, v70, v1
	v_mul_f32_e32 v15, v12, v7
	v_fma_f32 v56, -v3, v15, v12
	v_fmac_f32_e32 v15, v56, v7
	v_fma_f32 v3, -v3, v15, v12
	v_div_fmas_f32 v3, v3, v7, v15
	v_div_fixup_f32 v70, v3, v70, v1
	v_lshlrev_b32_e32 v1, 16, v73
	v_and_b32_e32 v3, 0xffff0000, v73
	v_mul_f32_e32 v7, 0xbfb8aa3b, v1
	v_exp_f32_e32 v72, v7
	v_mul_f32_e32 v7, 0xbfb8aa3b, v3
	v_exp_f32_e32 v73, v7
	s_nop 0
	v_pk_add_f32 v[72:73], v[72:73], 1.0 op_sel_hi:[1,0]
	s_nop 0
	v_div_scale_f32 v7, s[2:3], v73, v73, v3
	v_rcp_f32_e32 v12, v7
	s_nop 0
	v_fma_f32 v15, -v7, v12, 1.0
	v_fmac_f32_e32 v12, v15, v12
	v_div_scale_f32 v15, vcc, v3, v73, v3
	v_mul_f32_e32 v56, v15, v12
	v_fma_f32 v76, -v7, v56, v15
	v_fmac_f32_e32 v56, v76, v12
	v_mov_b64_e32 v[76:77], v[142:143]
	v_fma_f32 v7, -v7, v56, v15
	v_div_fmas_f32 v7, v7, v12, v56
	v_div_fixup_f32 v73, v7, v73, v3
	v_div_scale_f32 v3, s[2:3], v72, v72, v1
	v_rcp_f32_e32 v7, v3
	s_nop 0
	v_fma_f32 v12, -v3, v7, 1.0
	v_fmac_f32_e32 v7, v12, v7
	v_div_scale_f32 v12, vcc, v1, v72, v1
	v_mul_f32_e32 v15, v12, v7
	v_fma_f32 v56, -v3, v15, v12
	v_fmac_f32_e32 v15, v56, v7
	v_fma_f32 v3, -v3, v15, v12
	v_div_fmas_f32 v3, v3, v7, v15
	v_div_fixup_f32 v72, v3, v72, v1
	s_nop 0
	v_lshlrev_b32_e32 v1, 16, v76
	v_and_b32_e32 v3, 0xffff0000, v76
	v_mul_f32_e32 v7, 0xbfb8aa3b, v1
	v_exp_f32_e32 v74, v7
	v_mul_f32_e32 v7, 0xbfb8aa3b, v3
	v_exp_f32_e32 v75, v7
	s_nop 0
	v_pk_add_f32 v[74:75], v[74:75], 1.0 op_sel_hi:[1,0]
	s_nop 0
	v_div_scale_f32 v7, s[2:3], v75, v75, v3
	v_rcp_f32_e32 v12, v7
	s_nop 0
	v_fma_f32 v15, -v7, v12, 1.0
	v_fmac_f32_e32 v12, v15, v12
	v_div_scale_f32 v15, vcc, v3, v75, v3
	v_mul_f32_e32 v56, v15, v12
	v_fma_f32 v76, -v7, v56, v15
	v_fmac_f32_e32 v56, v76, v12
	v_fma_f32 v7, -v7, v56, v15
	v_div_fmas_f32 v7, v7, v12, v56
	v_div_fixup_f32 v75, v7, v75, v3
	v_div_scale_f32 v3, s[2:3], v74, v74, v1
	v_rcp_f32_e32 v7, v3
	s_nop 0
	v_fma_f32 v12, -v3, v7, 1.0
	v_fmac_f32_e32 v7, v12, v7
	v_div_scale_f32 v12, vcc, v1, v74, v1
	v_mul_f32_e32 v15, v12, v7
	v_fma_f32 v56, -v3, v15, v12
	v_fmac_f32_e32 v15, v56, v7
	v_fma_f32 v3, -v3, v15, v12
	v_div_fmas_f32 v3, v3, v7, v15
	v_div_fixup_f32 v74, v3, v74, v1
	v_lshlrev_b32_e32 v1, 16, v77
	v_and_b32_e32 v3, 0xffff0000, v77
	v_mul_f32_e32 v7, 0xbfb8aa3b, v1
	v_exp_f32_e32 v76, v7
	v_mul_f32_e32 v7, 0xbfb8aa3b, v3
	v_exp_f32_e32 v77, v7
	s_nop 0
	v_pk_add_f32 v[76:77], v[76:77], 1.0 op_sel_hi:[1,0]
	s_nop 0
	v_div_scale_f32 v7, s[2:3], v77, v77, v3
	v_rcp_f32_e32 v12, v7
	s_nop 0
	v_fma_f32 v15, -v7, v12, 1.0
	v_fmac_f32_e32 v12, v15, v12
	v_div_scale_f32 v15, vcc, v3, v77, v3
	v_mul_f32_e32 v56, v15, v12
	v_fma_f32 v78, -v7, v56, v15
	v_fmac_f32_e32 v56, v78, v12
	v_fma_f32 v7, -v7, v56, v15
	v_div_fmas_f32 v7, v7, v12, v56
	v_div_fixup_f32 v77, v7, v77, v3
	v_div_scale_f32 v3, s[2:3], v76, v76, v1
	v_rcp_f32_e32 v7, v3
	v_pk_mul_f32 v[78:79], v[34:35], v[34:35]
	s_mov_b32 s2, 0x3c800000
	v_pk_mov_b32 v[82:83], v[80:81], v[78:79] op_sel:[1,0]
	v_fma_f32 v12, -v3, v7, 1.0
	v_fmac_f32_e32 v7, v12, v7
	v_div_scale_f32 v12, vcc, v1, v76, v1
	v_mul_f32_e32 v15, v12, v7
	v_fma_f32 v56, -v3, v15, v12
	v_mov_b32_e32 v81, v79
	v_fmac_f32_e32 v15, v56, v7
	v_pk_add_f32 v[78:79], v[82:83], v[80:81]
	v_pk_mul_f32 v[80:81], v[30:31], v[30:31]
	v_pk_mul_f32 v[82:83], v[28:29], v[28:29]
	v_fma_f32 v3, -v3, v15, v12
	v_pk_mov_b32 v[84:85], v[82:83], v[80:81] op_sel:[1,0]
	v_mov_b32_e32 v83, v81
	v_div_fmas_f32 v3, v3, v7, v15
	v_pk_add_f32 v[80:81], v[84:85], v[82:83]
	v_div_fixup_f32 v76, v3, v76, v1
	v_mul_f32_e32 v1, v20, v20
	v_mul_f32_e32 v3, v21, v21
	v_pk_add_f32 v[78:79], v[78:79], v[78:79] op_sel:[0,1] op_sel_hi:[1,0]
	v_pk_add_f32 v[80:81], v[80:81], v[80:81] op_sel:[0,1] op_sel_hi:[1,0]
	v_mov_b32_e32 v79, v1
	v_mov_b32_e32 v81, v3
	v_mul_f32_e32 v12, v25, v25
	v_pk_add_f32 v[78:79], v[78:79], v[80:81]
	v_pk_fma_f32 v[80:81], v[24:25], v[24:25], v[12:13] op_sel_hi:[1,1,0]
	v_mul_f32_e32 v12, v27, v27
	v_mul_f32_e32 v7, v22, v22
	v_mul_f32_e32 v15, v23, v23
	v_pk_fma_f32 v[82:83], v[26:27], v[26:27], v[12:13] op_sel_hi:[1,1,0]
	v_mov_b32_e32 v81, v7
	v_mov_b32_e32 v83, v15
	v_pk_add_f32 v[80:81], v[80:81], v[82:83]
	s_nop 0
	v_pk_add_f32 v[78:79], v[78:79], v[80:81]
	s_nop 0
	v_pk_add_f32 v[78:79], v[78:79], v[78:79] op_sel:[0,1] op_sel_hi:[1,0]
	s_nop 0
	v_mov_b32_e32 v1, v78
	s_nop 1
	v_permlane16_swap_b32_e32 v78, v1
	v_add_f32_e32 v12, v78, v1
	v_mov_b32_e32 v56, v12
	s_nop 1
	v_permlane32_swap_b32_e32 v12, v56
	v_pk_add_f32 v[12:13], v[12:13], v[56:57]
	s_nop 0
	v_pk_fma_f32 v[12:13], v[12:13], s[2:3], v[196:197] op_sel_hi:[1,0,0]
	v_mad_i64_i32 v[4:5], s[2:3], v0, s93, v[4:5]
	v_mul_f32_e32 v1, 0x4b800000, v13
	v_cmp_gt_f32_e64 s[38:39], s22, v13
	v_cmp_gt_f32_e32 vcc, s22, v12
	v_lshl_add_u64 v[4:5], v[4:5], 0, v[8:9]
	v_cndmask_b32_e64 v1, v13, v1, s[38:39]
	v_rsq_f32_e32 v1, v1
	v_lshl_add_u64 v[4:5], v[4:5], 0, v[16:17]
	v_mul_f32_e32 v3, 0x45800000, v1
	v_cndmask_b32_e64 v56, v1, v3, s[38:39]
	v_pk_mul_f32 v[52:53], v[52:53], v[56:57] op_sel_hi:[1,0]
	v_pk_mul_f32 v[48:49], v[48:49], v[56:57] op_sel_hi:[1,0]
	v_pk_mul_f32 v[36:37], v[36:37], v[52:53]
	v_pk_mul_f32 v[52:53], v[54:55], v[56:57] op_sel_hi:[1,0]
	v_pk_mul_f32 v[36:37], v[58:59], v[36:37]
	v_pk_mul_f32 v[38:39], v[38:39], v[52:53]
	v_cvt_pk_bf16_f32 v36, v36, v37
	v_pk_mul_f32 v[38:39], v[62:63], v[38:39]
	v_pk_mul_f32 v[44:45], v[44:45], v[56:57] op_sel_hi:[1,0]
	v_cvt_pk_bf16_f32 v37, v38, v39
	v_add_co_u32_e64 v38, s[38:39], s27, v64
	v_mul_f32_e32 v1, 0x4b800000, v12
	s_nop 0
	v_addc_co_u32_e64 v39, s[38:39], 0, v65, s[38:39]
	global_store_dwordx2 v[38:39], v[36:37], off offset:1536
	s_nop 1
	v_mov_b64_e32 v[36:37], v[160:161]
	v_mov_b64_e32 v[38:39], v[162:163]
	v_cndmask_b32_e32 v1, v12, v1, vcc
	v_rsq_f32_e32 v1, v1
	v_pk_mul_f32 v[40:41], v[40:41], v[56:57] op_sel_hi:[1,0]
	v_mul_f32_e32 v3, 0x45800000, v1
	v_cndmask_b32_e32 v12, v1, v3, vcc
	v_ashrrev_i32_e32 v1, 31, v0
	v_lshlrev_b64 v[0:1], 11, v[0:1]
	v_lshl_add_u64 v[0:1], s[24:25], 0, v[0:1]
	v_lshl_add_u64 v[0:1], v[0:1], 0, v[8:9]
	v_lshl_add_u64 v[8:9], v[4:5], 0, s[8:9]
	v_add_co_u32_e32 v4, vcc, s94, v4
	v_pk_mul_f32 v[32:33], v[32:33], v[12:13] op_sel_hi:[1,0]
	s_nop 0
	v_addc_co_u32_e32 v5, vcc, 0, v5, vcc
	v_mov_b64_e32 v[4:5], v[144:145]
	v_lshl_add_u64 v[0:1], v[0:1], 0, v[16:17]
	v_lshl_add_u64 v[16:17], v[0:1], 0, s[10:11]
	s_nop 0
	v_pk_mul_f32 v[36:37], v[36:37], v[48:49]
	v_pk_mul_f32 v[48:49], v[50:51], v[56:57] op_sel_hi:[1,0]
	v_pk_mul_f32 v[36:37], v[36:37], v[66:67]
	v_pk_mul_f32 v[38:39], v[38:39], v[48:49]
	v_cvt_pk_bf16_f32 v36, v36, v37
	v_pk_mul_f32 v[38:39], v[38:39], v[68:69]
	s_nop 0
	v_lshlrev_b32_e32 v3, 16, v4
	v_cvt_pk_bf16_f32 v37, v38, v39
	global_store_dwordx2 v[60:61], v[36:37], off offset:32
	s_nop 1
	v_mov_b64_e32 v[36:37], v[164:165]
	v_mov_b64_e32 v[38:39], v[166:167]
	v_and_b32_e32 v4, 0xffff0000, v4
	v_mul_f32_e32 v7, 0xbfb8aa3b, v3
	s_nop 0
	v_pk_mul_f32 v[36:37], v[36:37], v[44:45]
	v_pk_mul_f32 v[44:45], v[46:47], v[56:57] op_sel_hi:[1,0]
	v_pk_mul_f32 v[36:37], v[36:37], v[70:71]
	v_pk_mul_f32 v[38:39], v[38:39], v[44:45]
	v_cvt_pk_bf16_f32 v36, v36, v37
	v_pk_mul_f32 v[38:39], v[38:39], v[72:73]
	s_nop 0
	v_cvt_pk_bf16_f32 v37, v38, v39
	global_store_dwordx2 v[60:61], v[36:37], off offset:64
	s_nop 1
	v_mov_b64_e32 v[36:37], v[168:169]
	v_mov_b64_e32 v[38:39], v[170:171]
	s_nop 0
	v_pk_mul_f32 v[36:37], v[36:37], v[40:41]
	v_pk_mul_f32 v[40:41], v[42:43], v[56:57] op_sel_hi:[1,0]
	v_pk_mul_f32 v[36:37], v[36:37], v[74:75]
	v_pk_mul_f32 v[38:39], v[38:39], v[40:41]
	v_cvt_pk_bf16_f32 v36, v36, v37
	v_pk_mul_f32 v[38:39], v[38:39], v[76:77]
	v_exp_f32_e32 v40, v7
	v_cvt_pk_bf16_f32 v37, v38, v39
	global_store_dwordx2 v[60:61], v[36:37], off offset:96
	s_nop 1
	v_mov_b64_e32 v[36:37], v[156:157]
	v_mov_b64_e32 v[38:39], v[158:159]
	v_mul_f32_e32 v7, 0xbfb8aa3b, v4
	v_exp_f32_e32 v41, v7
	s_nop 0
	v_pk_mul_f32 v[32:33], v[36:37], v[32:33]
	v_pk_add_f32 v[36:37], v[40:41], 1.0 op_sel_hi:[1,0]
	s_nop 0
	v_div_scale_f32 v7, s[2:3], v37, v37, v4
	v_rcp_f32_e32 v13, v7
	s_nop 0
	v_fma_f32 v15, -v7, v13, 1.0
	v_fmac_f32_e32 v13, v15, v13
	v_div_scale_f32 v15, vcc, v4, v37, v4
	v_mul_f32_e32 v40, v15, v13
	v_fma_f32 v41, -v7, v40, v15
	v_fmac_f32_e32 v40, v41, v13
	v_fma_f32 v7, -v7, v40, v15
	v_div_fmas_f32 v7, v7, v13, v40
	v_div_fixup_f32 v37, v7, v37, v4
	v_div_scale_f32 v4, s[2:3], v36, v36, v3
	v_rcp_f32_e32 v7, v4
	s_nop 0
	v_fma_f32 v13, -v4, v7, 1.0
	v_fmac_f32_e32 v7, v13, v7
	v_div_scale_f32 v13, vcc, v3, v36, v3
	v_mul_f32_e32 v15, v13, v7
	v_fma_f32 v40, -v4, v15, v13
	v_fmac_f32_e32 v15, v40, v7
	v_fma_f32 v4, -v4, v15, v13
	v_div_fmas_f32 v4, v4, v7, v15
	v_div_fixup_f32 v36, v4, v36, v3
	v_lshlrev_b32_e32 v3, 16, v5
	v_pk_mul_f32 v[32:33], v[36:37], v[32:33]
	v_and_b32_e32 v5, 0xffff0000, v5
	v_mul_f32_e32 v7, 0xbfb8aa3b, v3
	v_cvt_pk_bf16_f32 v4, v32, v33
	v_exp_f32_e32 v32, v7
	v_mul_f32_e32 v7, 0xbfb8aa3b, v5
	v_exp_f32_e32 v33, v7
	v_pk_mul_f32 v[34:35], v[34:35], v[12:13] op_sel_hi:[1,0]
	v_pk_add_f32 v[32:33], v[32:33], 1.0 op_sel_hi:[1,0]
	s_nop 0
	v_div_scale_f32 v7, s[2:3], v33, v33, v5
	v_rcp_f32_e32 v13, v7
	v_pk_mul_f32 v[34:35], v[38:39], v[34:35]
	v_fma_f32 v15, -v7, v13, 1.0
	v_fmac_f32_e32 v13, v15, v13
	v_div_scale_f32 v15, vcc, v5, v33, v5
	v_mul_f32_e32 v36, v15, v13
	v_fma_f32 v37, -v7, v36, v15
	v_fmac_f32_e32 v36, v37, v13
	v_fma_f32 v7, -v7, v36, v15
	v_div_fmas_f32 v7, v7, v13, v36
	v_div_fixup_f32 v33, v7, v33, v5
	v_div_scale_f32 v5, s[2:3], v32, v32, v3
	v_rcp_f32_e32 v7, v5
	s_nop 0
	v_fma_f32 v13, -v5, v7, 1.0
	v_fmac_f32_e32 v7, v13, v7
	v_div_scale_f32 v13, vcc, v3, v32, v3
	v_mul_f32_e32 v15, v13, v7
	v_fma_f32 v36, -v5, v15, v13
	v_fmac_f32_e32 v15, v36, v7
	v_fma_f32 v5, -v5, v15, v13
	v_div_fmas_f32 v5, v5, v7, v15
	v_div_fixup_f32 v32, v5, v32, v3
	v_pk_mul_f32 v[32:33], v[32:33], v[34:35]
	v_add_co_u32_e32 v0, vcc, s27, v0
	v_cvt_pk_bf16_f32 v5, v32, v33
	s_nop 0
	v_addc_co_u32_e32 v1, vcc, 0, v1, vcc
	global_store_dwordx2 v[0:1], v[4:5], off offset:1536
	s_nop 1
	v_mov_b64_e32 v[32:33], v[160:161]
	v_mov_b64_e32 v[34:35], v[162:163]
	s_nop 0
	v_mov_b64_e32 v[0:1], v[146:147]
	v_pk_mul_f32 v[28:29], v[28:29], v[12:13] op_sel_hi:[1,0]
	s_nop 0
	v_lshlrev_b32_e32 v3, 16, v0
	v_and_b32_e32 v0, 0xffff0000, v0
	v_mul_f32_e32 v4, 0xbfb8aa3b, v3
	v_mul_f32_e32 v5, 0xbfb8aa3b, v0
	v_exp_f32_e32 v4, v4
	v_exp_f32_e32 v5, v5
	v_pk_mul_f32 v[28:29], v[32:33], v[28:29]
	v_pk_add_f32 v[4:5], v[4:5], 1.0 op_sel_hi:[1,0]
	s_nop 0
	v_div_scale_f32 v7, s[2:3], v5, v5, v0
	v_rcp_f32_e32 v13, v7
	s_nop 0
	v_fma_f32 v15, -v7, v13, 1.0
	v_fmac_f32_e32 v13, v15, v13
	v_div_scale_f32 v15, vcc, v0, v5, v0
	v_mul_f32_e32 v32, v15, v13
	v_fma_f32 v33, -v7, v32, v15
	v_fmac_f32_e32 v32, v33, v13
	v_fma_f32 v7, -v7, v32, v15
	v_div_fmas_f32 v7, v7, v13, v32
	v_div_fixup_f32 v5, v7, v5, v0
	v_div_scale_f32 v0, s[2:3], v4, v4, v3
	v_rcp_f32_e32 v7, v0
	s_nop 0
	v_fma_f32 v13, -v0, v7, 1.0
	v_fmac_f32_e32 v7, v13, v7
	v_div_scale_f32 v13, vcc, v3, v4, v3
	v_mul_f32_e32 v15, v13, v7
	v_fma_f32 v32, -v0, v15, v13
	v_fmac_f32_e32 v15, v32, v7
	v_fma_f32 v0, -v0, v15, v13
	v_div_fmas_f32 v0, v0, v7, v15
	v_div_fixup_f32 v4, v0, v4, v3
	v_pk_mul_f32 v[4:5], v[28:29], v[4:5]
	v_lshlrev_b32_e32 v3, 16, v1
	v_and_b32_e32 v1, 0xffff0000, v1
	v_cvt_pk_bf16_f32 v0, v4, v5
	v_mul_f32_e32 v4, 0xbfb8aa3b, v3
	v_mul_f32_e32 v5, 0xbfb8aa3b, v1
	v_exp_f32_e32 v4, v4
	v_exp_f32_e32 v5, v5
	v_pk_mul_f32 v[28:29], v[30:31], v[12:13] op_sel_hi:[1,0]
	v_pk_add_f32 v[4:5], v[4:5], 1.0 op_sel_hi:[1,0]
	s_nop 0
	v_div_scale_f32 v7, s[2:3], v5, v5, v1
	v_rcp_f32_e32 v13, v7
	v_pk_mul_f32 v[28:29], v[34:35], v[28:29]
	v_fma_f32 v15, -v7, v13, 1.0
	v_fmac_f32_e32 v13, v15, v13
	v_div_scale_f32 v15, vcc, v1, v5, v1
	v_mul_f32_e32 v30, v15, v13
	v_fma_f32 v31, -v7, v30, v15
	v_fmac_f32_e32 v30, v31, v13
	v_fma_f32 v7, -v7, v30, v15
	v_div_fmas_f32 v7, v7, v13, v30
	v_div_fixup_f32 v5, v7, v5, v1
	v_div_scale_f32 v1, s[2:3], v4, v4, v3
	v_rcp_f32_e32 v7, v1
	s_nop 0
	v_fma_f32 v13, -v1, v7, 1.0
	v_fmac_f32_e32 v7, v13, v7
	v_div_scale_f32 v13, vcc, v3, v4, v3
	v_mul_f32_e32 v15, v13, v7
	v_fma_f32 v30, -v1, v15, v13
	v_fmac_f32_e32 v15, v30, v7
	v_fma_f32 v1, -v1, v15, v13
	v_div_fmas_f32 v1, v1, v7, v15
	v_div_fixup_f32 v4, v1, v4, v3
	v_pk_mul_f32 v[4:5], v[28:29], v[4:5]
	v_pk_mul_f32 v[24:25], v[24:25], v[12:13] op_sel_hi:[1,0]
	v_cvt_pk_bf16_f32 v1, v4, v5
	global_store_dwordx2 v[16:17], v[0:1], off offset:32
	s_nop 1
	v_mov_b64_e32 v[28:29], v[164:165]
	v_mov_b64_e32 v[30:31], v[166:167]
	s_nop 0
	v_mov_b64_e32 v[0:1], v[148:149]
	s_nop 0
	v_pk_mul_f32 v[24:25], v[28:29], v[24:25]
	s_nop 0
	v_lshlrev_b32_e32 v3, 16, v0
	v_and_b32_e32 v0, 0xffff0000, v0
	v_mul_f32_e32 v4, 0xbfb8aa3b, v3
	v_mul_f32_e32 v5, 0xbfb8aa3b, v0
	v_exp_f32_e32 v4, v4
	v_exp_f32_e32 v5, v5
	s_nop 0
	v_pk_add_f32 v[4:5], v[4:5], 1.0 op_sel_hi:[1,0]
	s_nop 0
	v_div_scale_f32 v7, s[2:3], v5, v5, v0
	v_rcp_f32_e32 v13, v7
	s_nop 0
	v_fma_f32 v15, -v7, v13, 1.0
	v_fmac_f32_e32 v13, v15, v13
	v_div_scale_f32 v15, vcc, v0, v5, v0
	v_mul_f32_e32 v28, v15, v13
	v_fma_f32 v29, -v7, v28, v15
	v_fmac_f32_e32 v28, v29, v13
	v_fma_f32 v7, -v7, v28, v15
	v_div_fmas_f32 v7, v7, v13, v28
	v_div_fixup_f32 v5, v7, v5, v0
	v_div_scale_f32 v0, s[2:3], v4, v4, v3
	v_rcp_f32_e32 v7, v0
	s_nop 0
	v_fma_f32 v13, -v0, v7, 1.0
	v_fmac_f32_e32 v7, v13, v7
	v_div_scale_f32 v13, vcc, v3, v4, v3
	v_mul_f32_e32 v15, v13, v7
	v_fma_f32 v28, -v0, v15, v13
	v_fmac_f32_e32 v15, v28, v7
	v_fma_f32 v0, -v0, v15, v13
	v_div_fmas_f32 v0, v0, v7, v15
	v_div_fixup_f32 v4, v0, v4, v3
	v_pk_mul_f32 v[4:5], v[24:25], v[4:5]
	v_lshlrev_b32_e32 v3, 16, v1
	v_and_b32_e32 v1, 0xffff0000, v1
	v_cvt_pk_bf16_f32 v0, v4, v5
	v_mul_f32_e32 v4, 0xbfb8aa3b, v3
	v_mul_f32_e32 v5, 0xbfb8aa3b, v1
	v_exp_f32_e32 v4, v4
	v_exp_f32_e32 v5, v5
	v_pk_mul_f32 v[24:25], v[26:27], v[12:13] op_sel_hi:[1,0]
	v_pk_add_f32 v[4:5], v[4:5], 1.0 op_sel_hi:[1,0]
	s_nop 0
	v_div_scale_f32 v7, s[2:3], v5, v5, v1
	v_rcp_f32_e32 v13, v7
	v_pk_mul_f32 v[24:25], v[30:31], v[24:25]
	v_fma_f32 v15, -v7, v13, 1.0
	v_fmac_f32_e32 v13, v15, v13
	v_div_scale_f32 v15, vcc, v1, v5, v1
	v_mul_f32_e32 v26, v15, v13
	v_fma_f32 v27, -v7, v26, v15
	v_fmac_f32_e32 v26, v27, v13
	v_fma_f32 v7, -v7, v26, v15
	v_div_fmas_f32 v7, v7, v13, v26
	v_div_fixup_f32 v5, v7, v5, v1
	v_div_scale_f32 v1, s[2:3], v4, v4, v3
	v_rcp_f32_e32 v7, v1
	s_nop 0
	v_fma_f32 v13, -v1, v7, 1.0
	v_fmac_f32_e32 v7, v13, v7
	v_div_scale_f32 v13, vcc, v3, v4, v3
	v_mul_f32_e32 v15, v13, v7
	v_fma_f32 v26, -v1, v15, v13
	v_fmac_f32_e32 v15, v26, v7
	v_fma_f32 v1, -v1, v15, v13
	v_div_fmas_f32 v1, v1, v7, v15
	v_div_fixup_f32 v4, v1, v4, v3
	v_pk_mul_f32 v[4:5], v[24:25], v[4:5]
	s_nop 0
	v_cvt_pk_bf16_f32 v1, v4, v5
	global_store_dwordx2 v[16:17], v[0:1], off offset:64
	s_nop 1
	v_mov_b64_e32 v[24:25], v[168:169]
	v_mov_b64_e32 v[26:27], v[170:171]
	s_nop 0
	v_mov_b64_e32 v[0:1], v[150:151]
	v_pk_mul_f32 v[8:9], v[20:21], v[12:13] op_sel_hi:[1,0]
	s_nop 0
	v_lshlrev_b32_e32 v3, 16, v0
	v_and_b32_e32 v0, 0xffff0000, v0
	v_mul_f32_e32 v4, 0xbfb8aa3b, v3
	v_mul_f32_e32 v5, 0xbfb8aa3b, v0
	v_exp_f32_e32 v4, v4
	v_exp_f32_e32 v5, v5
	v_pk_mul_f32 v[8:9], v[24:25], v[8:9]
	v_pk_add_f32 v[4:5], v[4:5], 1.0 op_sel_hi:[1,0]
	s_nop 0
	v_div_scale_f32 v7, s[2:3], v5, v5, v0
	v_rcp_f32_e32 v13, v7
	s_nop 0
	v_fma_f32 v15, -v7, v13, 1.0
	v_fmac_f32_e32 v13, v15, v13
	v_div_scale_f32 v15, vcc, v0, v5, v0
	v_mul_f32_e32 v19, v15, v13
	v_fma_f32 v20, -v7, v19, v15
	v_fmac_f32_e32 v19, v20, v13
	v_fma_f32 v7, -v7, v19, v15
	v_div_fmas_f32 v7, v7, v13, v19
	v_div_fixup_f32 v5, v7, v5, v0
	v_div_scale_f32 v0, s[2:3], v4, v4, v3
	v_rcp_f32_e32 v7, v0
	s_nop 0
	v_fma_f32 v13, -v0, v7, 1.0
	v_fmac_f32_e32 v7, v13, v7
	v_div_scale_f32 v13, vcc, v3, v4, v3
	v_mul_f32_e32 v15, v13, v7
	v_fma_f32 v19, -v0, v15, v13
	v_fmac_f32_e32 v15, v19, v7
	v_fma_f32 v0, -v0, v15, v13
	v_div_fmas_f32 v0, v0, v7, v15
	v_div_fixup_f32 v4, v0, v4, v3
	v_pk_mul_f32 v[4:5], v[8:9], v[4:5]
	v_lshlrev_b32_e32 v3, 16, v1
	v_and_b32_e32 v1, 0xffff0000, v1
	v_cvt_pk_bf16_f32 v0, v4, v5
	v_mul_f32_e32 v4, 0xbfb8aa3b, v3
	v_mul_f32_e32 v5, 0xbfb8aa3b, v1
	v_exp_f32_e32 v4, v4
	v_exp_f32_e32 v5, v5
	v_pk_mul_f32 v[8:9], v[22:23], v[12:13] op_sel_hi:[1,0]
	v_pk_add_f32 v[4:5], v[4:5], 1.0 op_sel_hi:[1,0]
	s_nop 0
	v_div_scale_f32 v7, s[2:3], v5, v5, v1
	v_rcp_f32_e32 v12, v7
	v_pk_mul_f32 v[8:9], v[26:27], v[8:9]
	v_fma_f32 v13, -v7, v12, 1.0
	v_fmac_f32_e32 v12, v13, v12
	v_div_scale_f32 v13, vcc, v1, v5, v1
	v_mul_f32_e32 v15, v13, v12
	v_fma_f32 v19, -v7, v15, v13
	v_fmac_f32_e32 v15, v19, v12
	v_fma_f32 v7, -v7, v15, v13
	v_div_fmas_f32 v7, v7, v12, v15
	v_div_fixup_f32 v5, v7, v5, v1
	v_div_scale_f32 v1, s[2:3], v4, v4, v3
	v_rcp_f32_e32 v7, v1
	v_readlane_b32 s2, v248, 4
	s_mov_b32 s38, s2
	v_fma_f32 v12, -v1, v7, 1.0
	v_fmac_f32_e32 v7, v12, v7
	v_div_scale_f32 v12, vcc, v3, v4, v3
	v_mul_f32_e32 v13, v12, v7
	v_fma_f32 v15, -v1, v13, v12
	v_fmac_f32_e32 v13, v15, v7
	v_fma_f32 v1, -v1, v13, v12
	v_div_fmas_f32 v1, v1, v7, v13
	v_div_fixup_f32 v4, v1, v4, v3
	v_pk_mul_f32 v[4:5], v[8:9], v[4:5]
	s_nop 0
	v_cvt_pk_bf16_f32 v1, v4, v5
	global_store_dwordx2 v[16:17], v[0:1], off offset:96
	s_cbranch_scc1 .LBB0_585
